# baseline (speedup 1.0000x reference)
; __device__ __forceinline__ float xor1f(float v) { return __int_as_float(__builtin_amdgcn_update_dpp(0, __float_as_int(v), 0xB1, 0xF, 0xF, true)); }
; template <int K, int EPI>
; __device__ __forceinline__ void gemm_tile(const u16* __restrict__ A, const u16* __restrict__ Bt, int brow, int bcol,
;                                           u16* Cb, int ldc, const float* R, float* Cf) {
;     ...
;   const int row0 = brow + wr * 64 + fq * 4, col0 = bcol + wc * 32 + fr;
;   if constexpr (EPI == 0) {
;     u16* cb = Cb + (size_t)row0 * ldc + col0;
; #pragma unroll
;     for (int ai = 0; ai < 2; ++ai)
; #pragma unroll
;       for (int m = 0; m < 4; ++m)
; #pragma unroll
;         for (int j = 0; j < 4; ++j) {
;           u16* cr = cb + (size_t)(ai * HALF + m * 16 + j) * ldc;
; #pragma unroll
;           for (int bj = 0; bj < 2; ++bj)
; #pragma unroll
;             for (int n = 0; n < 2; ++n) {
;               const float v = acc[ai][bj][m][n][j];
;               const float vn = xor1f(v);
;               if ((fr & 1) == 0) *(unsigned*)(cr + bj * HALF + n * 16) = cvtpk(v, vn);
;             }
;         }
.LBB0_167:
	s_lshl_b32 s4, s70, 8
	s_lshl_b32 s58, s71, 6
	s_lshl_b32 s3, s3, 5
	s_add_i32 s58, s58, s4
	s_or_b32 s2, s3, s2
	v_lshl_or_b32 v128, v143, 2, s58
	v_or_b32_e32 v130, s2, v142
	v_mov_b64_e32 v[132:133], s[42:43]
	v_mad_i64_i32 v[132:133], s[2:3], v128, s68, v[132:133]
	v_ashrrev_i32_e32 v131, 31, v130
	v_and_b32_e32 v128, 1, v141
	v_lshl_add_u64 v[130:131], v[130:131], 1, v[132:133]
	v_cmp_eq_u32_e64 s[2:3], 0, v128
	s_mov_b32 vcc_lo, 0x55555555
	s_mov_b32 vcc_hi, 0x55555555
	v_cndmask_b32_e64 v128, 30, 0, vcc
	v_add_co_u32_e64 v132, s[2:3], v128, v130
	s_mov_b32 s58, 0x5e00
	s_nop 1
	v_addc_co_u32_e64 v133, s[2:3], 0, v131, s[2:3]
	v_cndmask_b32_dpp v128, v116, v124, vcc quad_perm:[1,0,3,2] row_mask:0xf bank_mask:0xf
	v_mov_b32_dpp v130, v124 quad_perm:[1,0,3,2] row_mask:0xf bank_mask:0xf bound_ctrl:1
	v_cndmask_b32_e32 v130, v116, v130, vcc
	v_cvt_pk_bf16_f32 v128, v128, v130
	global_store_dword v[132:133], v128, off
	v_cndmask_b32_dpp v131, v112, v120, vcc quad_perm:[1,0,3,2] row_mask:0xf bank_mask:0xf
	v_mov_b32_dpp v124, v120 quad_perm:[1,0,3,2] row_mask:0xf bank_mask:0xf bound_ctrl:1
	v_cndmask_b32_e32 v124, v112, v124, vcc
	v_cvt_pk_bf16_f32 v131, v131, v124
	global_store_dword v[132:133], v131, off offset:256
	v_add_co_u32_e64 v132, s[2:3], s58, v132
	v_cndmask_b32_dpp v116, v117, v125, vcc quad_perm:[1,0,3,2] row_mask:0xf bank_mask:0xf
	v_mov_b32_dpp v128, v125 quad_perm:[1,0,3,2] row_mask:0xf bank_mask:0xf bound_ctrl:1
	v_cndmask_b32_e32 v128, v117, v128, vcc
	v_cvt_pk_bf16_f32 v116, v116, v128
	v_addc_co_u32_e64 v133, s[2:3], 0, v133, s[2:3]
	global_store_dword v[132:133], v116, off
	v_cndmask_b32_dpp v130, v113, v121, vcc quad_perm:[1,0,3,2] row_mask:0xf bank_mask:0xf
	v_mov_b32_dpp v120, v121 quad_perm:[1,0,3,2] row_mask:0xf bank_mask:0xf bound_ctrl:1
	v_cndmask_b32_e32 v120, v113, v120, vcc
	v_cvt_pk_bf16_f32 v130, v130, v120
	global_store_dword v[132:133], v130, off offset:256
	v_add_co_u32_e64 v132, s[2:3], s58, v132
	v_cndmask_b32_dpp v112, v118, v126, vcc quad_perm:[1,0,3,2] row_mask:0xf bank_mask:0xf
	v_mov_b32_dpp v131, v126 quad_perm:[1,0,3,2] row_mask:0xf bank_mask:0xf bound_ctrl:1
	v_cndmask_b32_e32 v131, v118, v131, vcc
	v_cvt_pk_bf16_f32 v112, v112, v131
	v_addc_co_u32_e64 v133, s[2:3], 0, v133, s[2:3]
	global_store_dword v[132:133], v112, off
	v_cndmask_b32_dpp v124, v114, v122, vcc quad_perm:[1,0,3,2] row_mask:0xf bank_mask:0xf
	v_mov_b32_dpp v125, v122 quad_perm:[1,0,3,2] row_mask:0xf bank_mask:0xf bound_ctrl:1
	v_cndmask_b32_e32 v125, v114, v125, vcc
	v_cvt_pk_bf16_f32 v124, v124, v125
	global_store_dword v[132:133], v124, off offset:256
	v_add_co_u32_e64 v132, s[2:3], s58, v132
	v_cndmask_b32_dpp v117, v119, v127, vcc quad_perm:[1,0,3,2] row_mask:0xf bank_mask:0xf
	v_mov_b32_dpp v116, v127 quad_perm:[1,0,3,2] row_mask:0xf bank_mask:0xf bound_ctrl:1
	v_cndmask_b32_e32 v116, v119, v116, vcc
	v_cvt_pk_bf16_f32 v117, v117, v116
	v_addc_co_u32_e64 v133, s[2:3], 0, v133, s[2:3]
	global_store_dword v[132:133], v117, off
	v_cndmask_b32_dpp v128, v115, v123, vcc quad_perm:[1,0,3,2] row_mask:0xf bank_mask:0xf
	v_mov_b32_dpp v121, v123 quad_perm:[1,0,3,2] row_mask:0xf bank_mask:0xf bound_ctrl:1
	v_cndmask_b32_e32 v121, v115, v121, vcc
	v_cvt_pk_bf16_f32 v128, v128, v121
	global_store_dword v[132:133], v128, off offset:256
	s_mov_b32 s58, 0x4c600
	v_add_co_u32_e64 v132, s[2:3], s58, v132
	v_cndmask_b32_dpp v113, v100, v108, vcc quad_perm:[1,0,3,2] row_mask:0xf bank_mask:0xf
	v_mov_b32_dpp v130, v108 quad_perm:[1,0,3,2] row_mask:0xf bank_mask:0xf bound_ctrl:1
	v_cndmask_b32_e32 v130, v100, v130, vcc
	v_cvt_pk_bf16_f32 v113, v113, v130
	v_addc_co_u32_e64 v133, s[2:3], 0, v133, s[2:3]
	global_store_dword v[132:133], v113, off
	v_cndmask_b32_dpp v120, v96, v104, vcc quad_perm:[1,0,3,2] row_mask:0xf bank_mask:0xf
	v_mov_b32_dpp v126, v104 quad_perm:[1,0,3,2] row_mask:0xf bank_mask:0xf bound_ctrl:1
	v_cndmask_b32_e32 v126, v96, v126, vcc
	v_cvt_pk_bf16_f32 v120, v120, v126
	global_store_dword v[132:133], v120, off offset:256
	s_mov_b32 s58, 0x5e00
	v_add_co_u32_e64 v132, s[2:3], s58, v132
	v_cndmask_b32_dpp v118, v101, v109, vcc quad_perm:[1,0,3,2] row_mask:0xf bank_mask:0xf
	v_mov_b32_dpp v112, v109 quad_perm:[1,0,3,2] row_mask:0xf bank_mask:0xf bound_ctrl:1
	v_cndmask_b32_e32 v112, v101, v112, vcc
	v_cvt_pk_bf16_f32 v118, v118, v112
	v_addc_co_u32_e64 v133, s[2:3], 0, v133, s[2:3]
	global_store_dword v[132:133], v118, off
	v_cndmask_b32_dpp v131, v97, v105, vcc quad_perm:[1,0,3,2] row_mask:0xf bank_mask:0xf
	v_mov_b32_dpp v122, v105 quad_perm:[1,0,3,2] row_mask:0xf bank_mask:0xf bound_ctrl:1
	v_cndmask_b32_e32 v122, v97, v122, vcc
	v_cvt_pk_bf16_f32 v131, v131, v122
	global_store_dword v[132:133], v131, off offset:256
	v_add_co_u32_e64 v132, s[2:3], s58, v132
	v_cndmask_b32_dpp v114, v102, v110, vcc quad_perm:[1,0,3,2] row_mask:0xf bank_mask:0xf
	v_mov_b32_dpp v124, v110 quad_perm:[1,0,3,2] row_mask:0xf bank_mask:0xf bound_ctrl:1
	v_cndmask_b32_e32 v124, v102, v124, vcc
	v_cvt_pk_bf16_f32 v114, v114, v124
	v_addc_co_u32_e64 v133, s[2:3], 0, v133, s[2:3]
	global_store_dword v[132:133], v114, off
	v_cndmask_b32_dpp v125, v98, v106, vcc quad_perm:[1,0,3,2] row_mask:0xf bank_mask:0xf
	v_mov_b32_dpp v127, v106 quad_perm:[1,0,3,2] row_mask:0xf bank_mask:0xf bound_ctrl:1
	v_cndmask_b32_e32 v127, v98, v127, vcc
	v_cvt_pk_bf16_f32 v125, v125, v127
	global_store_dword v[132:133], v125, off offset:256
	v_add_co_u32_e64 v132, s[2:3], s58, v132
	v_cndmask_b32_dpp v119, v103, v111, vcc quad_perm:[1,0,3,2] row_mask:0xf bank_mask:0xf
	v_mov_b32_dpp v117, v111 quad_perm:[1,0,3,2] row_mask:0xf bank_mask:0xf bound_ctrl:1
; __device__ __forceinline__ float xor1f(float v) { return __int_as_float(__builtin_amdgcn_update_dpp(0, __float_as_int(v), 0xB1, 0xF, 0xF, true)); }
; template <int K, int EPI>
; __device__ __forceinline__ void gemm_tile(const u16* __restrict__ A, const u16* __restrict__ Bt, int brow, int bcol,
;                                           u16* Cb, int ldc, const float* R, float* Cf) {
;     ...
;   const int row0 = brow + wr * 64 + fq * 4, col0 = bcol + wc * 32 + fr;
;   if constexpr (EPI == 0) {
;     u16* cb = Cb + (size_t)row0 * ldc + col0;
; #pragma unroll
;     for (int ai = 0; ai < 2; ++ai)
; #pragma unroll
;       for (int m = 0; m < 4; ++m)
; #pragma unroll
;         for (int j = 0; j < 4; ++j) {
;           u16* cr = cb + (size_t)(ai * HALF + m * 16 + j) * ldc;
; #pragma unroll
;           for (int bj = 0; bj < 2; ++bj)
; #pragma unroll
;             for (int n = 0; n < 2; ++n) {
;               const float v = acc[ai][bj][m][n][j];
;               const float vn = xor1f(v);
;               if ((fr & 1) == 0) *(unsigned*)(cr + bj * HALF + n * 16) = cvtpk(v, vn);
;             }
;         }
	v_cndmask_b32_e32 v117, v103, v117, vcc
	v_cvt_pk_bf16_f32 v119, v119, v117
	v_addc_co_u32_e64 v133, s[2:3], 0, v133, s[2:3]
	global_store_dword v[132:133], v119, off
	v_cndmask_b32_dpp v116, v99, v107, vcc quad_perm:[1,0,3,2] row_mask:0xf bank_mask:0xf
	v_mov_b32_dpp v123, v107 quad_perm:[1,0,3,2] row_mask:0xf bank_mask:0xf bound_ctrl:1
	v_cndmask_b32_e32 v123, v99, v123, vcc
	v_cvt_pk_bf16_f32 v116, v116, v123
	global_store_dword v[132:133], v116, off offset:256
	s_mov_b32 s58, 0x4c600
	v_add_co_u32_e64 v132, s[2:3], s58, v132
	v_cndmask_b32_dpp v115, v84, v92, vcc quad_perm:[1,0,3,2] row_mask:0xf bank_mask:0xf
	v_mov_b32_dpp v128, v92 quad_perm:[1,0,3,2] row_mask:0xf bank_mask:0xf bound_ctrl:1
	v_cndmask_b32_e32 v128, v84, v128, vcc
	v_cvt_pk_bf16_f32 v115, v115, v128
	v_addc_co_u32_e64 v133, s[2:3], 0, v133, s[2:3]
	global_store_dword v[132:133], v115, off
	v_cndmask_b32_dpp v121, v80, v88, vcc quad_perm:[1,0,3,2] row_mask:0xf bank_mask:0xf
	v_mov_b32_dpp v108, v88 quad_perm:[1,0,3,2] row_mask:0xf bank_mask:0xf bound_ctrl:1
	v_cndmask_b32_e32 v108, v80, v108, vcc
	v_cvt_pk_bf16_f32 v121, v121, v108
	global_store_dword v[132:133], v121, off offset:256
	s_mov_b32 s58, 0x5e00
	v_add_co_u32_e64 v132, s[2:3], s58, v132
	v_cndmask_b32_dpp v100, v85, v93, vcc quad_perm:[1,0,3,2] row_mask:0xf bank_mask:0xf
	v_mov_b32_dpp v113, v93 quad_perm:[1,0,3,2] row_mask:0xf bank_mask:0xf bound_ctrl:1
	v_cndmask_b32_e32 v113, v85, v113, vcc
	v_cvt_pk_bf16_f32 v100, v100, v113
	v_addc_co_u32_e64 v133, s[2:3], 0, v133, s[2:3]
	global_store_dword v[132:133], v100, off
	v_cndmask_b32_dpp v130, v81, v89, vcc quad_perm:[1,0,3,2] row_mask:0xf bank_mask:0xf
	v_mov_b32_dpp v104, v89 quad_perm:[1,0,3,2] row_mask:0xf bank_mask:0xf bound_ctrl:1
	v_cndmask_b32_e32 v104, v81, v104, vcc
	v_cvt_pk_bf16_f32 v130, v130, v104
	global_store_dword v[132:133], v130, off offset:256
	v_add_co_u32_e64 v132, s[2:3], s58, v132
	v_cndmask_b32_dpp v96, v86, v94, vcc quad_perm:[1,0,3,2] row_mask:0xf bank_mask:0xf
	v_mov_b32_dpp v120, v94 quad_perm:[1,0,3,2] row_mask:0xf bank_mask:0xf bound_ctrl:1
	v_cndmask_b32_e32 v120, v86, v120, vcc
	v_cvt_pk_bf16_f32 v96, v96, v120
	v_addc_co_u32_e64 v133, s[2:3], 0, v133, s[2:3]
	global_store_dword v[132:133], v96, off
	v_cndmask_b32_dpp v126, v82, v90, vcc quad_perm:[1,0,3,2] row_mask:0xf bank_mask:0xf
	v_mov_b32_dpp v109, v90 quad_perm:[1,0,3,2] row_mask:0xf bank_mask:0xf bound_ctrl:1
	v_cndmask_b32_e32 v109, v82, v109, vcc
	v_cvt_pk_bf16_f32 v126, v126, v109
	global_store_dword v[132:133], v126, off offset:256
	v_add_co_u32_e64 v132, s[2:3], s58, v132
	v_cndmask_b32_dpp v101, v87, v95, vcc quad_perm:[1,0,3,2] row_mask:0xf bank_mask:0xf
	v_mov_b32_dpp v118, v95 quad_perm:[1,0,3,2] row_mask:0xf bank_mask:0xf bound_ctrl:1
	v_cndmask_b32_e32 v118, v87, v118, vcc
	v_cvt_pk_bf16_f32 v101, v101, v118
	v_addc_co_u32_e64 v133, s[2:3], 0, v133, s[2:3]
	global_store_dword v[132:133], v101, off
	v_cndmask_b32_dpp v112, v83, v91, vcc quad_perm:[1,0,3,2] row_mask:0xf bank_mask:0xf
	v_mov_b32_dpp v105, v91 quad_perm:[1,0,3,2] row_mask:0xf bank_mask:0xf bound_ctrl:1
	v_cndmask_b32_e32 v105, v83, v105, vcc
	v_cvt_pk_bf16_f32 v112, v112, v105
	global_store_dword v[132:133], v112, off offset:256
	s_mov_b32 s58, 0x4c600
	v_add_co_u32_e64 v132, s[2:3], s58, v132
	v_cndmask_b32_dpp v97, v68, v76, vcc quad_perm:[1,0,3,2] row_mask:0xf bank_mask:0xf
	v_mov_b32_dpp v131, v76 quad_perm:[1,0,3,2] row_mask:0xf bank_mask:0xf bound_ctrl:1
	v_cndmask_b32_e32 v131, v68, v131, vcc
	v_cvt_pk_bf16_f32 v97, v97, v131
	v_addc_co_u32_e64 v133, s[2:3], 0, v133, s[2:3]
	global_store_dword v[132:133], v97, off
	v_cndmask_b32_dpp v122, v64, v72, vcc quad_perm:[1,0,3,2] row_mask:0xf bank_mask:0xf
	v_mov_b32_dpp v110, v72 quad_perm:[1,0,3,2] row_mask:0xf bank_mask:0xf bound_ctrl:1
	v_cndmask_b32_e32 v110, v64, v110, vcc
	v_cvt_pk_bf16_f32 v122, v122, v110
	global_store_dword v[132:133], v122, off offset:256
	s_mov_b32 s58, 0x5e00
	v_add_co_u32_e64 v132, s[2:3], s58, v132
	v_cndmask_b32_dpp v102, v69, v77, vcc quad_perm:[1,0,3,2] row_mask:0xf bank_mask:0xf
	v_mov_b32_dpp v114, v77 quad_perm:[1,0,3,2] row_mask:0xf bank_mask:0xf bound_ctrl:1
	v_cndmask_b32_e32 v114, v69, v114, vcc
	v_cvt_pk_bf16_f32 v102, v102, v114
	v_addc_co_u32_e64 v133, s[2:3], 0, v133, s[2:3]
	global_store_dword v[132:133], v102, off
	v_cndmask_b32_dpp v124, v65, v73, vcc quad_perm:[1,0,3,2] row_mask:0xf bank_mask:0xf
	v_mov_b32_dpp v106, v73 quad_perm:[1,0,3,2] row_mask:0xf bank_mask:0xf bound_ctrl:1
	v_cndmask_b32_e32 v106, v65, v106, vcc
	v_cvt_pk_bf16_f32 v124, v124, v106
	global_store_dword v[132:133], v124, off offset:256
	v_add_co_u32_e64 v132, s[2:3], s58, v132
	v_cndmask_b32_dpp v98, v70, v78, vcc quad_perm:[1,0,3,2] row_mask:0xf bank_mask:0xf
	v_mov_b32_dpp v125, v78 quad_perm:[1,0,3,2] row_mask:0xf bank_mask:0xf bound_ctrl:1
	v_cndmask_b32_e32 v125, v70, v125, vcc
	v_cvt_pk_bf16_f32 v98, v98, v125
	v_addc_co_u32_e64 v133, s[2:3], 0, v133, s[2:3]
	global_store_dword v[132:133], v98, off
	v_cndmask_b32_dpp v127, v66, v74, vcc quad_perm:[1,0,3,2] row_mask:0xf bank_mask:0xf
	v_mov_b32_dpp v111, v74 quad_perm:[1,0,3,2] row_mask:0xf bank_mask:0xf bound_ctrl:1
	v_cndmask_b32_e32 v111, v66, v111, vcc
	v_cvt_pk_bf16_f32 v127, v127, v111
	global_store_dword v[132:133], v127, off offset:256
	v_add_co_u32_e64 v132, s[2:3], s58, v132
	v_cndmask_b32_dpp v103, v71, v79, vcc quad_perm:[1,0,3,2] row_mask:0xf bank_mask:0xf
	v_mov_b32_dpp v119, v79 quad_perm:[1,0,3,2] row_mask:0xf bank_mask:0xf bound_ctrl:1
	v_cndmask_b32_e32 v119, v71, v119, vcc
	v_cvt_pk_bf16_f32 v103, v103, v119
	v_addc_co_u32_e64 v133, s[2:3], 0, v133, s[2:3]
; __device__ __forceinline__ float xor1f(float v) { return __int_as_float(__builtin_amdgcn_update_dpp(0, __float_as_int(v), 0xB1, 0xF, 0xF, true)); }
; template <int K, int EPI>
; __device__ __forceinline__ void gemm_tile(const u16* __restrict__ A, const u16* __restrict__ Bt, int brow, int bcol,
;                                           u16* Cb, int ldc, const float* R, float* Cf) {
;     ...
;   const int row0 = brow + wr * 64 + fq * 4, col0 = bcol + wc * 32 + fr;
;   if constexpr (EPI == 0) {
;     u16* cb = Cb + (size_t)row0 * ldc + col0;
; #pragma unroll
;     for (int ai = 0; ai < 2; ++ai)
; #pragma unroll
;       for (int m = 0; m < 4; ++m)
; #pragma unroll
;         for (int j = 0; j < 4; ++j) {
;           u16* cr = cb + (size_t)(ai * HALF + m * 16 + j) * ldc;
; #pragma unroll
;           for (int bj = 0; bj < 2; ++bj)
; #pragma unroll
;             for (int n = 0; n < 2; ++n) {
;               const float v = acc[ai][bj][m][n][j];
;               const float vn = xor1f(v);
;               if ((fr & 1) == 0) *(unsigned*)(cr + bj * HALF + n * 16) = cvtpk(v, vn);
;             }
;         }
	global_store_dword v[132:133], v103, off
	v_cndmask_b32_dpp v117, v67, v75, vcc quad_perm:[1,0,3,2] row_mask:0xf bank_mask:0xf
	v_mov_b32_dpp v107, v75 quad_perm:[1,0,3,2] row_mask:0xf bank_mask:0xf bound_ctrl:1
	v_cndmask_b32_e32 v107, v67, v107, vcc
	v_cvt_pk_bf16_f32 v117, v117, v107
	global_store_dword v[132:133], v117, off offset:256
	s_mov_b32 s58, 0x1c4600
	v_add_co_u32_e64 v132, s[2:3], s58, v132
	v_cndmask_b32_dpp v99, v56, v60, vcc quad_perm:[1,0,3,2] row_mask:0xf bank_mask:0xf
	v_mov_b32_dpp v116, v60 quad_perm:[1,0,3,2] row_mask:0xf bank_mask:0xf bound_ctrl:1
	v_cndmask_b32_e32 v116, v56, v116, vcc
	v_cvt_pk_bf16_f32 v99, v99, v116
	v_addc_co_u32_e64 v133, s[2:3], 0, v133, s[2:3]
	global_store_dword v[132:133], v99, off
	v_cndmask_b32_dpp v123, v48, v52, vcc quad_perm:[1,0,3,2] row_mask:0xf bank_mask:0xf
	v_mov_b32_dpp v92, v52 quad_perm:[1,0,3,2] row_mask:0xf bank_mask:0xf bound_ctrl:1
	v_cndmask_b32_e32 v92, v48, v92, vcc
	v_cvt_pk_bf16_f32 v123, v123, v92
	global_store_dword v[132:133], v123, off offset:256
	s_mov_b32 s58, 0x5e00
	v_add_co_u32_e64 v132, s[2:3], s58, v132
	v_cndmask_b32_dpp v84, v57, v61, vcc quad_perm:[1,0,3,2] row_mask:0xf bank_mask:0xf
	v_mov_b32_dpp v115, v61 quad_perm:[1,0,3,2] row_mask:0xf bank_mask:0xf bound_ctrl:1
	v_cndmask_b32_e32 v115, v57, v115, vcc
	v_cvt_pk_bf16_f32 v84, v84, v115
	v_addc_co_u32_e64 v133, s[2:3], 0, v133, s[2:3]
	global_store_dword v[132:133], v84, off
	v_cndmask_b32_dpp v128, v49, v53, vcc quad_perm:[1,0,3,2] row_mask:0xf bank_mask:0xf
	v_mov_b32_dpp v88, v53 quad_perm:[1,0,3,2] row_mask:0xf bank_mask:0xf bound_ctrl:1
	v_cndmask_b32_e32 v88, v49, v88, vcc
	v_cvt_pk_bf16_f32 v128, v128, v88
	global_store_dword v[132:133], v128, off offset:256
	v_add_co_u32_e64 v132, s[2:3], s58, v132
	v_cndmask_b32_dpp v80, v58, v62, vcc quad_perm:[1,0,3,2] row_mask:0xf bank_mask:0xf
	v_mov_b32_dpp v121, v62 quad_perm:[1,0,3,2] row_mask:0xf bank_mask:0xf bound_ctrl:1
	v_cndmask_b32_e32 v121, v58, v121, vcc
	v_cvt_pk_bf16_f32 v80, v80, v121
	v_addc_co_u32_e64 v133, s[2:3], 0, v133, s[2:3]
	global_store_dword v[132:133], v80, off
	v_cndmask_b32_dpp v108, v50, v54, vcc quad_perm:[1,0,3,2] row_mask:0xf bank_mask:0xf
	v_mov_b32_dpp v93, v54 quad_perm:[1,0,3,2] row_mask:0xf bank_mask:0xf bound_ctrl:1
	v_cndmask_b32_e32 v93, v50, v93, vcc
	v_cvt_pk_bf16_f32 v108, v108, v93
	global_store_dword v[132:133], v108, off offset:256
	v_add_co_u32_e64 v132, s[2:3], s58, v132
	v_cndmask_b32_dpp v85, v59, v63, vcc quad_perm:[1,0,3,2] row_mask:0xf bank_mask:0xf
	v_mov_b32_dpp v100, v63 quad_perm:[1,0,3,2] row_mask:0xf bank_mask:0xf bound_ctrl:1
	v_cndmask_b32_e32 v100, v59, v100, vcc
	v_cvt_pk_bf16_f32 v85, v85, v100
	v_addc_co_u32_e64 v133, s[2:3], 0, v133, s[2:3]
	global_store_dword v[132:133], v85, off
	v_cndmask_b32_dpp v113, v51, v55, vcc quad_perm:[1,0,3,2] row_mask:0xf bank_mask:0xf
	v_mov_b32_dpp v89, v55 quad_perm:[1,0,3,2] row_mask:0xf bank_mask:0xf bound_ctrl:1
	v_cndmask_b32_e32 v89, v51, v89, vcc
	v_cvt_pk_bf16_f32 v113, v113, v89
	global_store_dword v[132:133], v113, off offset:256
	s_mov_b32 s58, 0x4c600
	v_add_co_u32_e64 v132, s[2:3], s58, v132
	v_cndmask_b32_dpp v81, v40, v44, vcc quad_perm:[1,0,3,2] row_mask:0xf bank_mask:0xf
	v_mov_b32_dpp v130, v44 quad_perm:[1,0,3,2] row_mask:0xf bank_mask:0xf bound_ctrl:1
	v_cndmask_b32_e32 v130, v40, v130, vcc
	v_cvt_pk_bf16_f32 v81, v81, v130
	v_addc_co_u32_e64 v133, s[2:3], 0, v133, s[2:3]
	global_store_dword v[132:133], v81, off
	v_cndmask_b32_dpp v104, v32, v36, vcc quad_perm:[1,0,3,2] row_mask:0xf bank_mask:0xf
	v_mov_b32_dpp v94, v36 quad_perm:[1,0,3,2] row_mask:0xf bank_mask:0xf bound_ctrl:1
	v_cndmask_b32_e32 v94, v32, v94, vcc
	v_cvt_pk_bf16_f32 v104, v104, v94
	global_store_dword v[132:133], v104, off offset:256
	s_mov_b32 s58, 0x5e00
	v_add_co_u32_e64 v132, s[2:3], s58, v132
	v_cndmask_b32_dpp v86, v41, v45, vcc quad_perm:[1,0,3,2] row_mask:0xf bank_mask:0xf
	v_mov_b32_dpp v96, v45 quad_perm:[1,0,3,2] row_mask:0xf bank_mask:0xf bound_ctrl:1
	v_cndmask_b32_e32 v96, v41, v96, vcc
	v_cvt_pk_bf16_f32 v86, v86, v96
	v_addc_co_u32_e64 v133, s[2:3], 0, v133, s[2:3]
	global_store_dword v[132:133], v86, off
	v_cndmask_b32_dpp v120, v33, v37, vcc quad_perm:[1,0,3,2] row_mask:0xf bank_mask:0xf
	v_mov_b32_dpp v90, v37 quad_perm:[1,0,3,2] row_mask:0xf bank_mask:0xf bound_ctrl:1
	v_cndmask_b32_e32 v90, v33, v90, vcc
	v_cvt_pk_bf16_f32 v120, v120, v90
	global_store_dword v[132:133], v120, off offset:256
	v_add_co_u32_e64 v132, s[2:3], s58, v132
	v_cndmask_b32_dpp v82, v42, v46, vcc quad_perm:[1,0,3,2] row_mask:0xf bank_mask:0xf
	v_mov_b32_dpp v126, v46 quad_perm:[1,0,3,2] row_mask:0xf bank_mask:0xf bound_ctrl:1
	v_cndmask_b32_e32 v126, v42, v126, vcc
	v_cvt_pk_bf16_f32 v82, v82, v126
	v_addc_co_u32_e64 v133, s[2:3], 0, v133, s[2:3]
	global_store_dword v[132:133], v82, off
	v_cndmask_b32_dpp v109, v34, v38, vcc quad_perm:[1,0,3,2] row_mask:0xf bank_mask:0xf
	v_mov_b32_dpp v95, v38 quad_perm:[1,0,3,2] row_mask:0xf bank_mask:0xf bound_ctrl:1
	v_cndmask_b32_e32 v95, v34, v95, vcc
	v_cvt_pk_bf16_f32 v109, v109, v95
	global_store_dword v[132:133], v109, off offset:256
	v_add_co_u32_e64 v132, s[2:3], s58, v132
	v_cndmask_b32_dpp v87, v43, v47, vcc quad_perm:[1,0,3,2] row_mask:0xf bank_mask:0xf
	v_mov_b32_dpp v101, v47 quad_perm:[1,0,3,2] row_mask:0xf bank_mask:0xf bound_ctrl:1
	v_cndmask_b32_e32 v101, v43, v101, vcc
	v_cvt_pk_bf16_f32 v87, v87, v101
	v_addc_co_u32_e64 v133, s[2:3], 0, v133, s[2:3]
	global_store_dword v[132:133], v87, off
	v_cndmask_b32_dpp v118, v35, v39, vcc quad_perm:[1,0,3,2] row_mask:0xf bank_mask:0xf
; __device__ __forceinline__ float xor1f(float v) { return __int_as_float(__builtin_amdgcn_update_dpp(0, __float_as_int(v), 0xB1, 0xF, 0xF, true)); }
; template <int K, int EPI>
; __device__ __forceinline__ void gemm_tile(const u16* __restrict__ A, const u16* __restrict__ Bt, int brow, int bcol,
;                                           u16* Cb, int ldc, const float* R, float* Cf) {
;     ...
;   const int row0 = brow + wr * 64 + fq * 4, col0 = bcol + wc * 32 + fr;
;   if constexpr (EPI == 0) {
;     u16* cb = Cb + (size_t)row0 * ldc + col0;
; #pragma unroll
;     for (int ai = 0; ai < 2; ++ai)
; #pragma unroll
;       for (int m = 0; m < 4; ++m)
; #pragma unroll
;         for (int j = 0; j < 4; ++j) {
;           u16* cr = cb + (size_t)(ai * HALF + m * 16 + j) * ldc;
; #pragma unroll
;           for (int bj = 0; bj < 2; ++bj)
; #pragma unroll
;             for (int n = 0; n < 2; ++n) {
;               const float v = acc[ai][bj][m][n][j];
;               const float vn = xor1f(v);
;               if ((fr & 1) == 0) *(unsigned*)(cr + bj * HALF + n * 16) = cvtpk(v, vn);
;             }
;         }
	v_mov_b32_dpp v91, v39 quad_perm:[1,0,3,2] row_mask:0xf bank_mask:0xf bound_ctrl:1
	v_cndmask_b32_e32 v91, v35, v91, vcc
	v_cvt_pk_bf16_f32 v118, v118, v91
	global_store_dword v[132:133], v118, off offset:256
	s_mov_b32 s58, 0x4c600
	v_add_co_u32_e64 v132, s[2:3], s58, v132
	v_cndmask_b32_dpp v83, v24, v28, vcc quad_perm:[1,0,3,2] row_mask:0xf bank_mask:0xf
	v_mov_b32_dpp v112, v28 quad_perm:[1,0,3,2] row_mask:0xf bank_mask:0xf bound_ctrl:1
	v_cndmask_b32_e32 v112, v24, v112, vcc
	v_cvt_pk_bf16_f32 v83, v83, v112
	v_addc_co_u32_e64 v133, s[2:3], 0, v133, s[2:3]
	global_store_dword v[132:133], v83, off
	v_cndmask_b32_dpp v105, v16, v20, vcc quad_perm:[1,0,3,2] row_mask:0xf bank_mask:0xf
	v_mov_b32_dpp v76, v20 quad_perm:[1,0,3,2] row_mask:0xf bank_mask:0xf bound_ctrl:1
	v_cndmask_b32_e32 v76, v16, v76, vcc
	v_cvt_pk_bf16_f32 v105, v105, v76
	global_store_dword v[132:133], v105, off offset:256
	s_mov_b32 s58, 0x5e00
	v_add_co_u32_e64 v132, s[2:3], s58, v132
	v_cndmask_b32_dpp v68, v25, v29, vcc quad_perm:[1,0,3,2] row_mask:0xf bank_mask:0xf
	v_mov_b32_dpp v97, v29 quad_perm:[1,0,3,2] row_mask:0xf bank_mask:0xf bound_ctrl:1
	v_cndmask_b32_e32 v97, v25, v97, vcc
	v_cvt_pk_bf16_f32 v68, v68, v97
	v_addc_co_u32_e64 v133, s[2:3], 0, v133, s[2:3]
	global_store_dword v[132:133], v68, off
	v_cndmask_b32_dpp v131, v17, v21, vcc quad_perm:[1,0,3,2] row_mask:0xf bank_mask:0xf
	v_mov_b32_dpp v72, v21 quad_perm:[1,0,3,2] row_mask:0xf bank_mask:0xf bound_ctrl:1
	v_cndmask_b32_e32 v72, v17, v72, vcc
	v_cvt_pk_bf16_f32 v131, v131, v72
	global_store_dword v[132:133], v131, off offset:256
	v_add_co_u32_e64 v132, s[2:3], s58, v132
	v_cndmask_b32_dpp v64, v26, v30, vcc quad_perm:[1,0,3,2] row_mask:0xf bank_mask:0xf
	v_mov_b32_dpp v122, v30 quad_perm:[1,0,3,2] row_mask:0xf bank_mask:0xf bound_ctrl:1
	v_cndmask_b32_e32 v122, v26, v122, vcc
	v_cvt_pk_bf16_f32 v64, v64, v122
	v_addc_co_u32_e64 v133, s[2:3], 0, v133, s[2:3]
	global_store_dword v[132:133], v64, off
	v_cndmask_b32_dpp v110, v18, v22, vcc quad_perm:[1,0,3,2] row_mask:0xf bank_mask:0xf
	v_mov_b32_dpp v77, v22 quad_perm:[1,0,3,2] row_mask:0xf bank_mask:0xf bound_ctrl:1
	v_cndmask_b32_e32 v77, v18, v77, vcc
	v_cvt_pk_bf16_f32 v110, v110, v77
	global_store_dword v[132:133], v110, off offset:256
	v_add_co_u32_e64 v132, s[2:3], s58, v132
	v_cndmask_b32_dpp v69, v27, v31, vcc quad_perm:[1,0,3,2] row_mask:0xf bank_mask:0xf
	v_mov_b32_dpp v102, v31 quad_perm:[1,0,3,2] row_mask:0xf bank_mask:0xf bound_ctrl:1
	v_cndmask_b32_e32 v102, v27, v102, vcc
	v_cvt_pk_bf16_f32 v69, v69, v102
	v_addc_co_u32_e64 v133, s[2:3], 0, v133, s[2:3]
	global_store_dword v[132:133], v69, off
	v_cndmask_b32_dpp v114, v19, v23, vcc quad_perm:[1,0,3,2] row_mask:0xf bank_mask:0xf
	v_mov_b32_dpp v73, v23 quad_perm:[1,0,3,2] row_mask:0xf bank_mask:0xf bound_ctrl:1
	v_cndmask_b32_e32 v73, v19, v73, vcc
	v_cvt_pk_bf16_f32 v114, v114, v73
	global_store_dword v[132:133], v114, off offset:256
	s_mov_b32 s58, 0x4c600
	v_add_co_u32_e64 v132, s[2:3], s58, v132
	v_cndmask_b32_dpp v65, v8, v12, vcc quad_perm:[1,0,3,2] row_mask:0xf bank_mask:0xf
	v_mov_b32_dpp v124, v12 quad_perm:[1,0,3,2] row_mask:0xf bank_mask:0xf bound_ctrl:1
	v_cndmask_b32_e32 v124, v8, v124, vcc
	v_cvt_pk_bf16_f32 v65, v65, v124
	v_addc_co_u32_e64 v133, s[2:3], 0, v133, s[2:3]
	global_store_dword v[132:133], v65, off
	v_cndmask_b32_dpp v106, v0, v4, vcc quad_perm:[1,0,3,2] row_mask:0xf bank_mask:0xf
	v_mov_b32_dpp v78, v4 quad_perm:[1,0,3,2] row_mask:0xf bank_mask:0xf bound_ctrl:1
	v_cndmask_b32_e32 v78, v0, v78, vcc
	v_cvt_pk_bf16_f32 v106, v106, v78
	global_store_dword v[132:133], v106, off offset:256
	s_mov_b32 s58, 0x5e00
	v_add_co_u32_e64 v132, s[2:3], s58, v132
	v_cndmask_b32_dpp v70, v9, v13, vcc quad_perm:[1,0,3,2] row_mask:0xf bank_mask:0xf
	v_mov_b32_dpp v98, v13 quad_perm:[1,0,3,2] row_mask:0xf bank_mask:0xf bound_ctrl:1
	v_cndmask_b32_e32 v98, v9, v98, vcc
	v_cvt_pk_bf16_f32 v70, v70, v98
	v_addc_co_u32_e64 v133, s[2:3], 0, v133, s[2:3]
	global_store_dword v[132:133], v70, off
	v_cndmask_b32_dpp v125, v1, v5, vcc quad_perm:[1,0,3,2] row_mask:0xf bank_mask:0xf
	v_mov_b32_dpp v74, v5 quad_perm:[1,0,3,2] row_mask:0xf bank_mask:0xf bound_ctrl:1
	v_cndmask_b32_e32 v74, v1, v74, vcc
	v_cvt_pk_bf16_f32 v125, v125, v74
	global_store_dword v[132:133], v125, off offset:256
	v_add_co_u32_e64 v132, s[2:3], s58, v132
	v_cndmask_b32_dpp v66, v10, v14, vcc quad_perm:[1,0,3,2] row_mask:0xf bank_mask:0xf
	v_mov_b32_dpp v127, v14 quad_perm:[1,0,3,2] row_mask:0xf bank_mask:0xf bound_ctrl:1
	v_cndmask_b32_e32 v127, v10, v127, vcc
	v_cvt_pk_bf16_f32 v66, v66, v127
	v_addc_co_u32_e64 v133, s[2:3], 0, v133, s[2:3]
	global_store_dword v[132:133], v66, off
	v_cndmask_b32_dpp v111, v2, v6, vcc quad_perm:[1,0,3,2] row_mask:0xf bank_mask:0xf
	v_mov_b32_dpp v79, v6 quad_perm:[1,0,3,2] row_mask:0xf bank_mask:0xf bound_ctrl:1
	v_cndmask_b32_e32 v79, v2, v79, vcc
	v_cvt_pk_bf16_f32 v111, v111, v79
	global_store_dword v[132:133], v111, off offset:256
	v_add_co_u32_e64 v132, s[2:3], s58, v132
	v_cndmask_b32_dpp v71, v11, v15, vcc quad_perm:[1,0,3,2] row_mask:0xf bank_mask:0xf
	v_mov_b32_dpp v103, v15 quad_perm:[1,0,3,2] row_mask:0xf bank_mask:0xf bound_ctrl:1
	v_cndmask_b32_e32 v103, v11, v103, vcc
	v_cvt_pk_bf16_f32 v71, v71, v103
	v_addc_co_u32_e64 v133, s[2:3], 0, v133, s[2:3]
	global_store_dword v[132:133], v71, off
	v_cndmask_b32_dpp v119, v3, v7, vcc quad_perm:[1,0,3,2] row_mask:0xf bank_mask:0xf
	v_mov_b32_dpp v75, v7 quad_perm:[1,0,3,2] row_mask:0xf bank_mask:0xf bound_ctrl:1
	v_cndmask_b32_e32 v75, v3, v75, vcc
	v_cvt_pk_bf16_f32 v119, v119, v75
	global_store_dword v[132:133], v119, off offset:256
	s_branch .LBB0_158

; __device__ __forceinline__ float xor1f(float v) { return __int_as_float(__builtin_amdgcn_update_dpp(0, __float_as_int(v), 0xB1, 0xF, 0xF, true)); }
; template <int K, int EPI>
; __device__ __forceinline__ void gemm_tile(const u16* __restrict__ A, const u16* __restrict__ Bt, int brow, int bcol,
;                                           u16* Cb, int ldc, const float* R, float* Cf) {
;     ...
;   const int row0 = brow + wr * 64 + fq * 4, col0 = bcol + wc * 32 + fr;
;   if constexpr (EPI == 0) {
;     u16* cb = Cb + (size_t)row0 * ldc + col0;
; #pragma unroll
;     for (int ai = 0; ai < 2; ++ai)
; #pragma unroll
;       for (int m = 0; m < 4; ++m)
; #pragma unroll
;         for (int j = 0; j < 4; ++j) {
;           u16* cr = cb + (size_t)(ai * HALF + m * 16 + j) * ldc;
; #pragma unroll
;           for (int bj = 0; bj < 2; ++bj)
; #pragma unroll
;             for (int n = 0; n < 2; ++n) {
;               const float v = acc[ai][bj][m][n][j];
;               const float vn = xor1f(v);
;               if ((fr & 1) == 0) *(unsigned*)(cr + bj * HALF + n * 16) = cvtpk(v, vn);
;             }
;         }
.LBB0_559:
	s_lshl_b32 s4, s74, 8
	s_lshl_b32 s62, s75, 6
	s_lshl_b32 s3, s3, 5
	s_add_i32 s62, s62, s4
	s_or_b32 s2, s3, s2
	v_lshl_or_b32 v128, v145, 2, s62
	v_or_b32_e32 v130, s2, v144
	v_mov_b64_e32 v[132:133], s[14:15]
	s_movk_i32 s2, 0x1800
	v_mad_i64_i32 v[132:133], s[2:3], v128, s2, v[132:133]
	v_ashrrev_i32_e32 v131, 31, v130
	v_and_b32_e32 v128, 1, v143
	v_lshl_add_u64 v[130:131], v[130:131], 1, v[132:133]
	v_cmp_eq_u32_e64 s[2:3], 0, v128
	s_mov_b32 vcc_lo, 0x55555555
	s_mov_b32 vcc_hi, 0x55555555
	v_cndmask_b32_e64 v128, 30, 0, vcc
	v_add_co_u32_e64 v132, s[2:3], v128, v130
	s_mov_b32 s62, 0x1800
	s_nop 1
	v_addc_co_u32_e64 v133, s[2:3], 0, v131, s[2:3]
	v_cndmask_b32_dpp v128, v116, v124, vcc quad_perm:[1,0,3,2] row_mask:0xf bank_mask:0xf
	v_mov_b32_dpp v130, v124 quad_perm:[1,0,3,2] row_mask:0xf bank_mask:0xf bound_ctrl:1
	v_cndmask_b32_e32 v130, v116, v130, vcc
	v_cvt_pk_bf16_f32 v128, v128, v130
	global_store_dword v[132:133], v128, off
	v_cndmask_b32_dpp v131, v112, v120, vcc quad_perm:[1,0,3,2] row_mask:0xf bank_mask:0xf
	v_mov_b32_dpp v124, v120 quad_perm:[1,0,3,2] row_mask:0xf bank_mask:0xf bound_ctrl:1
	v_cndmask_b32_e32 v124, v112, v124, vcc
	v_cvt_pk_bf16_f32 v131, v131, v124
	global_store_dword v[132:133], v131, off offset:256
	v_add_co_u32_e64 v132, s[2:3], s62, v132
	v_cndmask_b32_dpp v116, v117, v125, vcc quad_perm:[1,0,3,2] row_mask:0xf bank_mask:0xf
	v_mov_b32_dpp v128, v125 quad_perm:[1,0,3,2] row_mask:0xf bank_mask:0xf bound_ctrl:1
	v_cndmask_b32_e32 v128, v117, v128, vcc
	v_cvt_pk_bf16_f32 v116, v116, v128
	v_addc_co_u32_e64 v133, s[2:3], 0, v133, s[2:3]
	global_store_dword v[132:133], v116, off
	v_cndmask_b32_dpp v130, v113, v121, vcc quad_perm:[1,0,3,2] row_mask:0xf bank_mask:0xf
	v_mov_b32_dpp v120, v121 quad_perm:[1,0,3,2] row_mask:0xf bank_mask:0xf bound_ctrl:1
	v_cndmask_b32_e32 v120, v113, v120, vcc
	v_cvt_pk_bf16_f32 v130, v130, v120
	global_store_dword v[132:133], v130, off offset:256
	v_add_co_u32_e64 v132, s[2:3], s62, v132
	v_cndmask_b32_dpp v112, v118, v126, vcc quad_perm:[1,0,3,2] row_mask:0xf bank_mask:0xf
	v_mov_b32_dpp v131, v126 quad_perm:[1,0,3,2] row_mask:0xf bank_mask:0xf bound_ctrl:1
	v_cndmask_b32_e32 v131, v118, v131, vcc
	v_cvt_pk_bf16_f32 v112, v112, v131
	v_addc_co_u32_e64 v133, s[2:3], 0, v133, s[2:3]
	global_store_dword v[132:133], v112, off
	v_cndmask_b32_dpp v124, v114, v122, vcc quad_perm:[1,0,3,2] row_mask:0xf bank_mask:0xf
	v_mov_b32_dpp v125, v122 quad_perm:[1,0,3,2] row_mask:0xf bank_mask:0xf bound_ctrl:1
	v_cndmask_b32_e32 v125, v114, v125, vcc
	v_cvt_pk_bf16_f32 v124, v124, v125
	global_store_dword v[132:133], v124, off offset:256
	v_add_co_u32_e64 v132, s[2:3], s62, v132
	v_cndmask_b32_dpp v117, v119, v127, vcc quad_perm:[1,0,3,2] row_mask:0xf bank_mask:0xf
	v_mov_b32_dpp v116, v127 quad_perm:[1,0,3,2] row_mask:0xf bank_mask:0xf bound_ctrl:1
	v_cndmask_b32_e32 v116, v119, v116, vcc
	v_cvt_pk_bf16_f32 v117, v117, v116
	v_addc_co_u32_e64 v133, s[2:3], 0, v133, s[2:3]
	global_store_dword v[132:133], v117, off
	v_cndmask_b32_dpp v128, v115, v123, vcc quad_perm:[1,0,3,2] row_mask:0xf bank_mask:0xf
	v_mov_b32_dpp v121, v123 quad_perm:[1,0,3,2] row_mask:0xf bank_mask:0xf bound_ctrl:1
	v_cndmask_b32_e32 v121, v115, v121, vcc
	v_cvt_pk_bf16_f32 v128, v128, v121
	global_store_dword v[132:133], v128, off offset:256
	s_mov_b32 s62, 0x13800
	v_add_co_u32_e64 v132, s[2:3], s62, v132
	v_cndmask_b32_dpp v113, v100, v108, vcc quad_perm:[1,0,3,2] row_mask:0xf bank_mask:0xf
	v_mov_b32_dpp v130, v108 quad_perm:[1,0,3,2] row_mask:0xf bank_mask:0xf bound_ctrl:1
	v_cndmask_b32_e32 v130, v100, v130, vcc
	v_cvt_pk_bf16_f32 v113, v113, v130
	v_addc_co_u32_e64 v133, s[2:3], 0, v133, s[2:3]
	global_store_dword v[132:133], v113, off
	v_cndmask_b32_dpp v120, v96, v104, vcc quad_perm:[1,0,3,2] row_mask:0xf bank_mask:0xf
	v_mov_b32_dpp v126, v104 quad_perm:[1,0,3,2] row_mask:0xf bank_mask:0xf bound_ctrl:1
	v_cndmask_b32_e32 v126, v96, v126, vcc
	v_cvt_pk_bf16_f32 v120, v120, v126
	global_store_dword v[132:133], v120, off offset:256
	s_mov_b32 s62, 0x1800
	v_add_co_u32_e64 v132, s[2:3], s62, v132
	v_cndmask_b32_dpp v118, v101, v109, vcc quad_perm:[1,0,3,2] row_mask:0xf bank_mask:0xf
	v_mov_b32_dpp v112, v109 quad_perm:[1,0,3,2] row_mask:0xf bank_mask:0xf bound_ctrl:1
	v_cndmask_b32_e32 v112, v101, v112, vcc
	v_cvt_pk_bf16_f32 v118, v118, v112
	v_addc_co_u32_e64 v133, s[2:3], 0, v133, s[2:3]
	global_store_dword v[132:133], v118, off
	v_cndmask_b32_dpp v131, v97, v105, vcc quad_perm:[1,0,3,2] row_mask:0xf bank_mask:0xf
	v_mov_b32_dpp v122, v105 quad_perm:[1,0,3,2] row_mask:0xf bank_mask:0xf bound_ctrl:1
	v_cndmask_b32_e32 v122, v97, v122, vcc
	v_cvt_pk_bf16_f32 v131, v131, v122
	global_store_dword v[132:133], v131, off offset:256
	v_add_co_u32_e64 v132, s[2:3], s62, v132
	v_cndmask_b32_dpp v114, v102, v110, vcc quad_perm:[1,0,3,2] row_mask:0xf bank_mask:0xf
	v_mov_b32_dpp v124, v110 quad_perm:[1,0,3,2] row_mask:0xf bank_mask:0xf bound_ctrl:1
	v_cndmask_b32_e32 v124, v102, v124, vcc
	v_cvt_pk_bf16_f32 v114, v114, v124
	v_addc_co_u32_e64 v133, s[2:3], 0, v133, s[2:3]
	global_store_dword v[132:133], v114, off
	v_cndmask_b32_dpp v125, v98, v106, vcc quad_perm:[1,0,3,2] row_mask:0xf bank_mask:0xf
	v_mov_b32_dpp v127, v106 quad_perm:[1,0,3,2] row_mask:0xf bank_mask:0xf bound_ctrl:1
	v_cndmask_b32_e32 v127, v98, v127, vcc
	v_cvt_pk_bf16_f32 v125, v125, v127
	global_store_dword v[132:133], v125, off offset:256
	v_add_co_u32_e64 v132, s[2:3], s62, v132
	v_cndmask_b32_dpp v119, v103, v111, vcc quad_perm:[1,0,3,2] row_mask:0xf bank_mask:0xf
	v_mov_b32_dpp v117, v111 quad_perm:[1,0,3,2] row_mask:0xf bank_mask:0xf bound_ctrl:1
; __device__ __forceinline__ float xor1f(float v) { return __int_as_float(__builtin_amdgcn_update_dpp(0, __float_as_int(v), 0xB1, 0xF, 0xF, true)); }
; template <int K, int EPI>
; __device__ __forceinline__ void gemm_tile(const u16* __restrict__ A, const u16* __restrict__ Bt, int brow, int bcol,
;                                           u16* Cb, int ldc, const float* R, float* Cf) {
;     ...
;   const int row0 = brow + wr * 64 + fq * 4, col0 = bcol + wc * 32 + fr;
;   if constexpr (EPI == 0) {
;     u16* cb = Cb + (size_t)row0 * ldc + col0;
; #pragma unroll
;     for (int ai = 0; ai < 2; ++ai)
; #pragma unroll
;       for (int m = 0; m < 4; ++m)
; #pragma unroll
;         for (int j = 0; j < 4; ++j) {
;           u16* cr = cb + (size_t)(ai * HALF + m * 16 + j) * ldc;
; #pragma unroll
;           for (int bj = 0; bj < 2; ++bj)
; #pragma unroll
;             for (int n = 0; n < 2; ++n) {
;               const float v = acc[ai][bj][m][n][j];
;               const float vn = xor1f(v);
;               if ((fr & 1) == 0) *(unsigned*)(cr + bj * HALF + n * 16) = cvtpk(v, vn);
;             }
;         }
	v_cndmask_b32_e32 v117, v103, v117, vcc
	v_cvt_pk_bf16_f32 v119, v119, v117
	v_addc_co_u32_e64 v133, s[2:3], 0, v133, s[2:3]
	global_store_dword v[132:133], v119, off
	v_cndmask_b32_dpp v116, v99, v107, vcc quad_perm:[1,0,3,2] row_mask:0xf bank_mask:0xf
	v_mov_b32_dpp v123, v107 quad_perm:[1,0,3,2] row_mask:0xf bank_mask:0xf bound_ctrl:1
	v_cndmask_b32_e32 v123, v99, v123, vcc
	v_cvt_pk_bf16_f32 v116, v116, v123
	global_store_dword v[132:133], v116, off offset:256
	s_mov_b32 s62, 0x13800
	v_add_co_u32_e64 v132, s[2:3], s62, v132
	v_cndmask_b32_dpp v115, v84, v92, vcc quad_perm:[1,0,3,2] row_mask:0xf bank_mask:0xf
	v_mov_b32_dpp v128, v92 quad_perm:[1,0,3,2] row_mask:0xf bank_mask:0xf bound_ctrl:1
	v_cndmask_b32_e32 v128, v84, v128, vcc
	v_cvt_pk_bf16_f32 v115, v115, v128
	v_addc_co_u32_e64 v133, s[2:3], 0, v133, s[2:3]
	global_store_dword v[132:133], v115, off
	v_cndmask_b32_dpp v121, v80, v88, vcc quad_perm:[1,0,3,2] row_mask:0xf bank_mask:0xf
	v_mov_b32_dpp v108, v88 quad_perm:[1,0,3,2] row_mask:0xf bank_mask:0xf bound_ctrl:1
	v_cndmask_b32_e32 v108, v80, v108, vcc
	v_cvt_pk_bf16_f32 v121, v121, v108
	global_store_dword v[132:133], v121, off offset:256
	s_mov_b32 s62, 0x1800
	v_add_co_u32_e64 v132, s[2:3], s62, v132
	v_cndmask_b32_dpp v100, v85, v93, vcc quad_perm:[1,0,3,2] row_mask:0xf bank_mask:0xf
	v_mov_b32_dpp v113, v93 quad_perm:[1,0,3,2] row_mask:0xf bank_mask:0xf bound_ctrl:1
	v_cndmask_b32_e32 v113, v85, v113, vcc
	v_cvt_pk_bf16_f32 v100, v100, v113
	v_addc_co_u32_e64 v133, s[2:3], 0, v133, s[2:3]
	global_store_dword v[132:133], v100, off
	v_cndmask_b32_dpp v130, v81, v89, vcc quad_perm:[1,0,3,2] row_mask:0xf bank_mask:0xf
	v_mov_b32_dpp v104, v89 quad_perm:[1,0,3,2] row_mask:0xf bank_mask:0xf bound_ctrl:1
	v_cndmask_b32_e32 v104, v81, v104, vcc
	v_cvt_pk_bf16_f32 v130, v130, v104
	global_store_dword v[132:133], v130, off offset:256
	v_add_co_u32_e64 v132, s[2:3], s62, v132
	v_cndmask_b32_dpp v96, v86, v94, vcc quad_perm:[1,0,3,2] row_mask:0xf bank_mask:0xf
	v_mov_b32_dpp v120, v94 quad_perm:[1,0,3,2] row_mask:0xf bank_mask:0xf bound_ctrl:1
	v_cndmask_b32_e32 v120, v86, v120, vcc
	v_cvt_pk_bf16_f32 v96, v96, v120
	v_addc_co_u32_e64 v133, s[2:3], 0, v133, s[2:3]
	global_store_dword v[132:133], v96, off
	v_cndmask_b32_dpp v126, v82, v90, vcc quad_perm:[1,0,3,2] row_mask:0xf bank_mask:0xf
	v_mov_b32_dpp v109, v90 quad_perm:[1,0,3,2] row_mask:0xf bank_mask:0xf bound_ctrl:1
	v_cndmask_b32_e32 v109, v82, v109, vcc
	v_cvt_pk_bf16_f32 v126, v126, v109
	global_store_dword v[132:133], v126, off offset:256
	v_add_co_u32_e64 v132, s[2:3], s62, v132
	v_cndmask_b32_dpp v101, v87, v95, vcc quad_perm:[1,0,3,2] row_mask:0xf bank_mask:0xf
	v_mov_b32_dpp v118, v95 quad_perm:[1,0,3,2] row_mask:0xf bank_mask:0xf bound_ctrl:1
	v_cndmask_b32_e32 v118, v87, v118, vcc
	v_cvt_pk_bf16_f32 v101, v101, v118
	v_addc_co_u32_e64 v133, s[2:3], 0, v133, s[2:3]
	global_store_dword v[132:133], v101, off
	v_cndmask_b32_dpp v112, v83, v91, vcc quad_perm:[1,0,3,2] row_mask:0xf bank_mask:0xf
	v_mov_b32_dpp v105, v91 quad_perm:[1,0,3,2] row_mask:0xf bank_mask:0xf bound_ctrl:1
	v_cndmask_b32_e32 v105, v83, v105, vcc
	v_cvt_pk_bf16_f32 v112, v112, v105
	global_store_dword v[132:133], v112, off offset:256
	s_mov_b32 s62, 0x13800
	v_add_co_u32_e64 v132, s[2:3], s62, v132
	v_cndmask_b32_dpp v97, v68, v76, vcc quad_perm:[1,0,3,2] row_mask:0xf bank_mask:0xf
	v_mov_b32_dpp v131, v76 quad_perm:[1,0,3,2] row_mask:0xf bank_mask:0xf bound_ctrl:1
	v_cndmask_b32_e32 v131, v68, v131, vcc
	v_cvt_pk_bf16_f32 v97, v97, v131
	v_addc_co_u32_e64 v133, s[2:3], 0, v133, s[2:3]
	global_store_dword v[132:133], v97, off
	v_cndmask_b32_dpp v122, v64, v72, vcc quad_perm:[1,0,3,2] row_mask:0xf bank_mask:0xf
	v_mov_b32_dpp v110, v72 quad_perm:[1,0,3,2] row_mask:0xf bank_mask:0xf bound_ctrl:1
	v_cndmask_b32_e32 v110, v64, v110, vcc
	v_cvt_pk_bf16_f32 v122, v122, v110
	global_store_dword v[132:133], v122, off offset:256
	s_mov_b32 s62, 0x1800
	v_add_co_u32_e64 v132, s[2:3], s62, v132
	v_cndmask_b32_dpp v102, v69, v77, vcc quad_perm:[1,0,3,2] row_mask:0xf bank_mask:0xf
	v_mov_b32_dpp v114, v77 quad_perm:[1,0,3,2] row_mask:0xf bank_mask:0xf bound_ctrl:1
	v_cndmask_b32_e32 v114, v69, v114, vcc
	v_cvt_pk_bf16_f32 v102, v102, v114
	v_addc_co_u32_e64 v133, s[2:3], 0, v133, s[2:3]
	global_store_dword v[132:133], v102, off
	v_cndmask_b32_dpp v124, v65, v73, vcc quad_perm:[1,0,3,2] row_mask:0xf bank_mask:0xf
	v_mov_b32_dpp v106, v73 quad_perm:[1,0,3,2] row_mask:0xf bank_mask:0xf bound_ctrl:1
	v_cndmask_b32_e32 v106, v65, v106, vcc
	v_cvt_pk_bf16_f32 v124, v124, v106
	global_store_dword v[132:133], v124, off offset:256
	v_add_co_u32_e64 v132, s[2:3], s62, v132
	v_cndmask_b32_dpp v98, v70, v78, vcc quad_perm:[1,0,3,2] row_mask:0xf bank_mask:0xf
	v_mov_b32_dpp v125, v78 quad_perm:[1,0,3,2] row_mask:0xf bank_mask:0xf bound_ctrl:1
	v_cndmask_b32_e32 v125, v70, v125, vcc
	v_cvt_pk_bf16_f32 v98, v98, v125
	v_addc_co_u32_e64 v133, s[2:3], 0, v133, s[2:3]
	global_store_dword v[132:133], v98, off
	v_cndmask_b32_dpp v127, v66, v74, vcc quad_perm:[1,0,3,2] row_mask:0xf bank_mask:0xf
	v_mov_b32_dpp v111, v74 quad_perm:[1,0,3,2] row_mask:0xf bank_mask:0xf bound_ctrl:1
	v_cndmask_b32_e32 v111, v66, v111, vcc
	v_cvt_pk_bf16_f32 v127, v127, v111
	global_store_dword v[132:133], v127, off offset:256
	v_add_co_u32_e64 v132, s[2:3], s62, v132
	v_cndmask_b32_dpp v103, v71, v79, vcc quad_perm:[1,0,3,2] row_mask:0xf bank_mask:0xf
	v_mov_b32_dpp v119, v79 quad_perm:[1,0,3,2] row_mask:0xf bank_mask:0xf bound_ctrl:1
	v_cndmask_b32_e32 v119, v71, v119, vcc
	v_cvt_pk_bf16_f32 v103, v103, v119
	v_addc_co_u32_e64 v133, s[2:3], 0, v133, s[2:3]
; __device__ __forceinline__ float xor1f(float v) { return __int_as_float(__builtin_amdgcn_update_dpp(0, __float_as_int(v), 0xB1, 0xF, 0xF, true)); }
; template <int K, int EPI>
; __device__ __forceinline__ void gemm_tile(const u16* __restrict__ A, const u16* __restrict__ Bt, int brow, int bcol,
;                                           u16* Cb, int ldc, const float* R, float* Cf) {
;     ...
;   const int row0 = brow + wr * 64 + fq * 4, col0 = bcol + wc * 32 + fr;
;   if constexpr (EPI == 0) {
;     u16* cb = Cb + (size_t)row0 * ldc + col0;
; #pragma unroll
;     for (int ai = 0; ai < 2; ++ai)
; #pragma unroll
;       for (int m = 0; m < 4; ++m)
; #pragma unroll
;         for (int j = 0; j < 4; ++j) {
;           u16* cr = cb + (size_t)(ai * HALF + m * 16 + j) * ldc;
; #pragma unroll
;           for (int bj = 0; bj < 2; ++bj)
; #pragma unroll
;             for (int n = 0; n < 2; ++n) {
;               const float v = acc[ai][bj][m][n][j];
;               const float vn = xor1f(v);
;               if ((fr & 1) == 0) *(unsigned*)(cr + bj * HALF + n * 16) = cvtpk(v, vn);
;             }
;         }
	global_store_dword v[132:133], v103, off
	v_cndmask_b32_dpp v117, v67, v75, vcc quad_perm:[1,0,3,2] row_mask:0xf bank_mask:0xf
	v_mov_b32_dpp v107, v75 quad_perm:[1,0,3,2] row_mask:0xf bank_mask:0xf bound_ctrl:1
	v_cndmask_b32_e32 v107, v67, v107, vcc
	v_cvt_pk_bf16_f32 v117, v117, v107
	global_store_dword v[132:133], v117, off offset:256
	s_mov_b32 s62, 0x73800
	v_add_co_u32_e64 v132, s[2:3], s62, v132
	v_cndmask_b32_dpp v99, v56, v60, vcc quad_perm:[1,0,3,2] row_mask:0xf bank_mask:0xf
	v_mov_b32_dpp v116, v60 quad_perm:[1,0,3,2] row_mask:0xf bank_mask:0xf bound_ctrl:1
	v_cndmask_b32_e32 v116, v56, v116, vcc
	v_cvt_pk_bf16_f32 v99, v99, v116
	v_addc_co_u32_e64 v133, s[2:3], 0, v133, s[2:3]
	global_store_dword v[132:133], v99, off
	v_cndmask_b32_dpp v123, v48, v52, vcc quad_perm:[1,0,3,2] row_mask:0xf bank_mask:0xf
	v_mov_b32_dpp v92, v52 quad_perm:[1,0,3,2] row_mask:0xf bank_mask:0xf bound_ctrl:1
	v_cndmask_b32_e32 v92, v48, v92, vcc
	v_cvt_pk_bf16_f32 v123, v123, v92
	global_store_dword v[132:133], v123, off offset:256
	s_mov_b32 s62, 0x1800
	v_add_co_u32_e64 v132, s[2:3], s62, v132
	v_cndmask_b32_dpp v84, v57, v61, vcc quad_perm:[1,0,3,2] row_mask:0xf bank_mask:0xf
	v_mov_b32_dpp v115, v61 quad_perm:[1,0,3,2] row_mask:0xf bank_mask:0xf bound_ctrl:1
	v_cndmask_b32_e32 v115, v57, v115, vcc
	v_cvt_pk_bf16_f32 v84, v84, v115
	v_addc_co_u32_e64 v133, s[2:3], 0, v133, s[2:3]
	global_store_dword v[132:133], v84, off
	v_cndmask_b32_dpp v128, v49, v53, vcc quad_perm:[1,0,3,2] row_mask:0xf bank_mask:0xf
	v_mov_b32_dpp v88, v53 quad_perm:[1,0,3,2] row_mask:0xf bank_mask:0xf bound_ctrl:1
	v_cndmask_b32_e32 v88, v49, v88, vcc
	v_cvt_pk_bf16_f32 v128, v128, v88
	global_store_dword v[132:133], v128, off offset:256
	v_add_co_u32_e64 v132, s[2:3], s62, v132
	v_cndmask_b32_dpp v80, v58, v62, vcc quad_perm:[1,0,3,2] row_mask:0xf bank_mask:0xf
	v_mov_b32_dpp v121, v62 quad_perm:[1,0,3,2] row_mask:0xf bank_mask:0xf bound_ctrl:1
	v_cndmask_b32_e32 v121, v58, v121, vcc
	v_cvt_pk_bf16_f32 v80, v80, v121
	v_addc_co_u32_e64 v133, s[2:3], 0, v133, s[2:3]
	global_store_dword v[132:133], v80, off
	v_cndmask_b32_dpp v108, v50, v54, vcc quad_perm:[1,0,3,2] row_mask:0xf bank_mask:0xf
	v_mov_b32_dpp v93, v54 quad_perm:[1,0,3,2] row_mask:0xf bank_mask:0xf bound_ctrl:1
	v_cndmask_b32_e32 v93, v50, v93, vcc
	v_cvt_pk_bf16_f32 v108, v108, v93
	global_store_dword v[132:133], v108, off offset:256
	v_add_co_u32_e64 v132, s[2:3], s62, v132
	v_cndmask_b32_dpp v85, v59, v63, vcc quad_perm:[1,0,3,2] row_mask:0xf bank_mask:0xf
	v_mov_b32_dpp v100, v63 quad_perm:[1,0,3,2] row_mask:0xf bank_mask:0xf bound_ctrl:1
	v_cndmask_b32_e32 v100, v59, v100, vcc
	v_cvt_pk_bf16_f32 v85, v85, v100
	v_addc_co_u32_e64 v133, s[2:3], 0, v133, s[2:3]
	global_store_dword v[132:133], v85, off
	v_cndmask_b32_dpp v113, v51, v55, vcc quad_perm:[1,0,3,2] row_mask:0xf bank_mask:0xf
	v_mov_b32_dpp v89, v55 quad_perm:[1,0,3,2] row_mask:0xf bank_mask:0xf bound_ctrl:1
	v_cndmask_b32_e32 v89, v51, v89, vcc
	v_cvt_pk_bf16_f32 v113, v113, v89
	global_store_dword v[132:133], v113, off offset:256
	s_mov_b32 s62, 0x13800
	v_add_co_u32_e64 v132, s[2:3], s62, v132
	v_cndmask_b32_dpp v81, v40, v44, vcc quad_perm:[1,0,3,2] row_mask:0xf bank_mask:0xf
	v_mov_b32_dpp v130, v44 quad_perm:[1,0,3,2] row_mask:0xf bank_mask:0xf bound_ctrl:1
	v_cndmask_b32_e32 v130, v40, v130, vcc
	v_cvt_pk_bf16_f32 v81, v81, v130
	v_addc_co_u32_e64 v133, s[2:3], 0, v133, s[2:3]
	global_store_dword v[132:133], v81, off
	v_cndmask_b32_dpp v104, v32, v36, vcc quad_perm:[1,0,3,2] row_mask:0xf bank_mask:0xf
	v_mov_b32_dpp v94, v36 quad_perm:[1,0,3,2] row_mask:0xf bank_mask:0xf bound_ctrl:1
	v_cndmask_b32_e32 v94, v32, v94, vcc
	v_cvt_pk_bf16_f32 v104, v104, v94
	global_store_dword v[132:133], v104, off offset:256
	s_mov_b32 s62, 0x1800
	v_add_co_u32_e64 v132, s[2:3], s62, v132
	v_cndmask_b32_dpp v86, v41, v45, vcc quad_perm:[1,0,3,2] row_mask:0xf bank_mask:0xf
	v_mov_b32_dpp v96, v45 quad_perm:[1,0,3,2] row_mask:0xf bank_mask:0xf bound_ctrl:1
	v_cndmask_b32_e32 v96, v41, v96, vcc
	v_cvt_pk_bf16_f32 v86, v86, v96
	v_addc_co_u32_e64 v133, s[2:3], 0, v133, s[2:3]
	global_store_dword v[132:133], v86, off
	v_cndmask_b32_dpp v120, v33, v37, vcc quad_perm:[1,0,3,2] row_mask:0xf bank_mask:0xf
	v_mov_b32_dpp v90, v37 quad_perm:[1,0,3,2] row_mask:0xf bank_mask:0xf bound_ctrl:1
	v_cndmask_b32_e32 v90, v33, v90, vcc
	v_cvt_pk_bf16_f32 v120, v120, v90
	global_store_dword v[132:133], v120, off offset:256
	v_add_co_u32_e64 v132, s[2:3], s62, v132
	v_cndmask_b32_dpp v82, v42, v46, vcc quad_perm:[1,0,3,2] row_mask:0xf bank_mask:0xf
	v_mov_b32_dpp v126, v46 quad_perm:[1,0,3,2] row_mask:0xf bank_mask:0xf bound_ctrl:1
	v_cndmask_b32_e32 v126, v42, v126, vcc
	v_cvt_pk_bf16_f32 v82, v82, v126
	v_addc_co_u32_e64 v133, s[2:3], 0, v133, s[2:3]
	global_store_dword v[132:133], v82, off
	v_cndmask_b32_dpp v109, v34, v38, vcc quad_perm:[1,0,3,2] row_mask:0xf bank_mask:0xf
	v_mov_b32_dpp v95, v38 quad_perm:[1,0,3,2] row_mask:0xf bank_mask:0xf bound_ctrl:1
	v_cndmask_b32_e32 v95, v34, v95, vcc
	v_cvt_pk_bf16_f32 v109, v109, v95
	global_store_dword v[132:133], v109, off offset:256
	v_add_co_u32_e64 v132, s[2:3], s62, v132
	v_cndmask_b32_dpp v87, v43, v47, vcc quad_perm:[1,0,3,2] row_mask:0xf bank_mask:0xf
	v_mov_b32_dpp v101, v47 quad_perm:[1,0,3,2] row_mask:0xf bank_mask:0xf bound_ctrl:1
	v_cndmask_b32_e32 v101, v43, v101, vcc
	v_cvt_pk_bf16_f32 v87, v87, v101
	v_addc_co_u32_e64 v133, s[2:3], 0, v133, s[2:3]
	global_store_dword v[132:133], v87, off
	v_cndmask_b32_dpp v118, v35, v39, vcc quad_perm:[1,0,3,2] row_mask:0xf bank_mask:0xf
; __device__ __forceinline__ float xor1f(float v) { return __int_as_float(__builtin_amdgcn_update_dpp(0, __float_as_int(v), 0xB1, 0xF, 0xF, true)); }
; template <int K, int EPI>
; __device__ __forceinline__ void gemm_tile(const u16* __restrict__ A, const u16* __restrict__ Bt, int brow, int bcol,
;                                           u16* Cb, int ldc, const float* R, float* Cf) {
;     ...
;   const int row0 = brow + wr * 64 + fq * 4, col0 = bcol + wc * 32 + fr;
;   if constexpr (EPI == 0) {
;     u16* cb = Cb + (size_t)row0 * ldc + col0;
; #pragma unroll
;     for (int ai = 0; ai < 2; ++ai)
; #pragma unroll
;       for (int m = 0; m < 4; ++m)
; #pragma unroll
;         for (int j = 0; j < 4; ++j) {
;           u16* cr = cb + (size_t)(ai * HALF + m * 16 + j) * ldc;
; #pragma unroll
;           for (int bj = 0; bj < 2; ++bj)
; #pragma unroll
;             for (int n = 0; n < 2; ++n) {
;               const float v = acc[ai][bj][m][n][j];
;               const float vn = xor1f(v);
;               if ((fr & 1) == 0) *(unsigned*)(cr + bj * HALF + n * 16) = cvtpk(v, vn);
;             }
;         }
	v_mov_b32_dpp v91, v39 quad_perm:[1,0,3,2] row_mask:0xf bank_mask:0xf bound_ctrl:1
	v_cndmask_b32_e32 v91, v35, v91, vcc
	v_cvt_pk_bf16_f32 v118, v118, v91
	global_store_dword v[132:133], v118, off offset:256
	s_mov_b32 s62, 0x13800
	v_add_co_u32_e64 v132, s[2:3], s62, v132
	v_cndmask_b32_dpp v83, v24, v28, vcc quad_perm:[1,0,3,2] row_mask:0xf bank_mask:0xf
	v_mov_b32_dpp v112, v28 quad_perm:[1,0,3,2] row_mask:0xf bank_mask:0xf bound_ctrl:1
	v_cndmask_b32_e32 v112, v24, v112, vcc
	v_cvt_pk_bf16_f32 v83, v83, v112
	v_addc_co_u32_e64 v133, s[2:3], 0, v133, s[2:3]
	global_store_dword v[132:133], v83, off
	v_cndmask_b32_dpp v105, v16, v20, vcc quad_perm:[1,0,3,2] row_mask:0xf bank_mask:0xf
	v_mov_b32_dpp v76, v20 quad_perm:[1,0,3,2] row_mask:0xf bank_mask:0xf bound_ctrl:1
	v_cndmask_b32_e32 v76, v16, v76, vcc
	v_cvt_pk_bf16_f32 v105, v105, v76
	global_store_dword v[132:133], v105, off offset:256
	s_mov_b32 s62, 0x1800
	v_add_co_u32_e64 v132, s[2:3], s62, v132
	v_cndmask_b32_dpp v68, v25, v29, vcc quad_perm:[1,0,3,2] row_mask:0xf bank_mask:0xf
	v_mov_b32_dpp v97, v29 quad_perm:[1,0,3,2] row_mask:0xf bank_mask:0xf bound_ctrl:1
	v_cndmask_b32_e32 v97, v25, v97, vcc
	v_cvt_pk_bf16_f32 v68, v68, v97
	v_addc_co_u32_e64 v133, s[2:3], 0, v133, s[2:3]
	global_store_dword v[132:133], v68, off
	v_cndmask_b32_dpp v131, v17, v21, vcc quad_perm:[1,0,3,2] row_mask:0xf bank_mask:0xf
	v_mov_b32_dpp v72, v21 quad_perm:[1,0,3,2] row_mask:0xf bank_mask:0xf bound_ctrl:1
	v_cndmask_b32_e32 v72, v17, v72, vcc
	v_cvt_pk_bf16_f32 v131, v131, v72
	global_store_dword v[132:133], v131, off offset:256
	v_add_co_u32_e64 v132, s[2:3], s62, v132
	v_cndmask_b32_dpp v64, v26, v30, vcc quad_perm:[1,0,3,2] row_mask:0xf bank_mask:0xf
	v_mov_b32_dpp v122, v30 quad_perm:[1,0,3,2] row_mask:0xf bank_mask:0xf bound_ctrl:1
	v_cndmask_b32_e32 v122, v26, v122, vcc
	v_cvt_pk_bf16_f32 v64, v64, v122
	v_addc_co_u32_e64 v133, s[2:3], 0, v133, s[2:3]
	global_store_dword v[132:133], v64, off
	v_cndmask_b32_dpp v110, v18, v22, vcc quad_perm:[1,0,3,2] row_mask:0xf bank_mask:0xf
	v_mov_b32_dpp v77, v22 quad_perm:[1,0,3,2] row_mask:0xf bank_mask:0xf bound_ctrl:1
	v_cndmask_b32_e32 v77, v18, v77, vcc
	v_cvt_pk_bf16_f32 v110, v110, v77
	global_store_dword v[132:133], v110, off offset:256
	v_add_co_u32_e64 v132, s[2:3], s62, v132
	v_cndmask_b32_dpp v69, v27, v31, vcc quad_perm:[1,0,3,2] row_mask:0xf bank_mask:0xf
	v_mov_b32_dpp v102, v31 quad_perm:[1,0,3,2] row_mask:0xf bank_mask:0xf bound_ctrl:1
	v_cndmask_b32_e32 v102, v27, v102, vcc
	v_cvt_pk_bf16_f32 v69, v69, v102
	v_addc_co_u32_e64 v133, s[2:3], 0, v133, s[2:3]
	global_store_dword v[132:133], v69, off
	v_cndmask_b32_dpp v114, v19, v23, vcc quad_perm:[1,0,3,2] row_mask:0xf bank_mask:0xf
	v_mov_b32_dpp v73, v23 quad_perm:[1,0,3,2] row_mask:0xf bank_mask:0xf bound_ctrl:1
	v_cndmask_b32_e32 v73, v19, v73, vcc
	v_cvt_pk_bf16_f32 v114, v114, v73
	global_store_dword v[132:133], v114, off offset:256
	s_mov_b32 s62, 0x13800
	v_add_co_u32_e64 v132, s[2:3], s62, v132
	v_cndmask_b32_dpp v65, v8, v12, vcc quad_perm:[1,0,3,2] row_mask:0xf bank_mask:0xf
	v_mov_b32_dpp v124, v12 quad_perm:[1,0,3,2] row_mask:0xf bank_mask:0xf bound_ctrl:1
	v_cndmask_b32_e32 v124, v8, v124, vcc
	v_cvt_pk_bf16_f32 v65, v65, v124
	v_addc_co_u32_e64 v133, s[2:3], 0, v133, s[2:3]
	global_store_dword v[132:133], v65, off
	v_cndmask_b32_dpp v106, v0, v4, vcc quad_perm:[1,0,3,2] row_mask:0xf bank_mask:0xf
	v_mov_b32_dpp v78, v4 quad_perm:[1,0,3,2] row_mask:0xf bank_mask:0xf bound_ctrl:1
	v_cndmask_b32_e32 v78, v0, v78, vcc
	v_cvt_pk_bf16_f32 v106, v106, v78
	global_store_dword v[132:133], v106, off offset:256
	s_mov_b32 s62, 0x1800
	v_add_co_u32_e64 v132, s[2:3], s62, v132
	v_cndmask_b32_dpp v70, v9, v13, vcc quad_perm:[1,0,3,2] row_mask:0xf bank_mask:0xf
	v_mov_b32_dpp v98, v13 quad_perm:[1,0,3,2] row_mask:0xf bank_mask:0xf bound_ctrl:1
	v_cndmask_b32_e32 v98, v9, v98, vcc
	v_cvt_pk_bf16_f32 v70, v70, v98
	v_addc_co_u32_e64 v133, s[2:3], 0, v133, s[2:3]
	global_store_dword v[132:133], v70, off
	v_cndmask_b32_dpp v125, v1, v5, vcc quad_perm:[1,0,3,2] row_mask:0xf bank_mask:0xf
	v_mov_b32_dpp v74, v5 quad_perm:[1,0,3,2] row_mask:0xf bank_mask:0xf bound_ctrl:1
	v_cndmask_b32_e32 v74, v1, v74, vcc
	v_cvt_pk_bf16_f32 v125, v125, v74
	global_store_dword v[132:133], v125, off offset:256
	v_add_co_u32_e64 v132, s[2:3], s62, v132
	v_cndmask_b32_dpp v66, v10, v14, vcc quad_perm:[1,0,3,2] row_mask:0xf bank_mask:0xf
	v_mov_b32_dpp v127, v14 quad_perm:[1,0,3,2] row_mask:0xf bank_mask:0xf bound_ctrl:1
	v_cndmask_b32_e32 v127, v10, v127, vcc
	v_cvt_pk_bf16_f32 v66, v66, v127
	v_addc_co_u32_e64 v133, s[2:3], 0, v133, s[2:3]
	global_store_dword v[132:133], v66, off
	v_cndmask_b32_dpp v111, v2, v6, vcc quad_perm:[1,0,3,2] row_mask:0xf bank_mask:0xf
	v_mov_b32_dpp v79, v6 quad_perm:[1,0,3,2] row_mask:0xf bank_mask:0xf bound_ctrl:1
	v_cndmask_b32_e32 v79, v2, v79, vcc
	v_cvt_pk_bf16_f32 v111, v111, v79
	global_store_dword v[132:133], v111, off offset:256
	v_add_co_u32_e64 v132, s[2:3], s62, v132
	v_cndmask_b32_dpp v71, v11, v15, vcc quad_perm:[1,0,3,2] row_mask:0xf bank_mask:0xf
	v_mov_b32_dpp v103, v15 quad_perm:[1,0,3,2] row_mask:0xf bank_mask:0xf bound_ctrl:1
	v_cndmask_b32_e32 v103, v11, v103, vcc
	v_cvt_pk_bf16_f32 v71, v71, v103
	v_addc_co_u32_e64 v133, s[2:3], 0, v133, s[2:3]
	global_store_dword v[132:133], v71, off
	v_cndmask_b32_dpp v119, v3, v7, vcc quad_perm:[1,0,3,2] row_mask:0xf bank_mask:0xf
	v_mov_b32_dpp v75, v7 quad_perm:[1,0,3,2] row_mask:0xf bank_mask:0xf bound_ctrl:1
	v_cndmask_b32_e32 v75, v3, v75, vcc
	v_cvt_pk_bf16_f32 v119, v119, v75
	global_store_dword v[132:133], v119, off offset:256
	s_branch .LBB0_550

; __device__ __forceinline__ float xor1f(float v) { return __int_as_float(__builtin_amdgcn_update_dpp(0, __float_as_int(v), 0xB1, 0xF, 0xF, true)); }
; template <int K, int EPI>
; __device__ __forceinline__ void gemm_tile(const u16* __restrict__ A, const u16* __restrict__ Bt, int brow, int bcol,
;                                           u16* Cb, int ldc, const float* R, float* Cf) {
;     ...
;   const int row0 = brow + wr * 64 + fq * 4, col0 = bcol + wc * 32 + fr;
;   if constexpr (EPI == 0) {
;     u16* cb = Cb + (size_t)row0 * ldc + col0;
; #pragma unroll
;     for (int ai = 0; ai < 2; ++ai)
; #pragma unroll
;       for (int m = 0; m < 4; ++m)
; #pragma unroll
;         for (int j = 0; j < 4; ++j) {
;           u16* cr = cb + (size_t)(ai * HALF + m * 16 + j) * ldc;
; #pragma unroll
;           for (int bj = 0; bj < 2; ++bj)
; #pragma unroll
;             for (int n = 0; n < 2; ++n) {
;               const float v = acc[ai][bj][m][n][j];
;               const float vn = xor1f(v);
;               if ((fr & 1) == 0) *(unsigned*)(cr + bj * HALF + n * 16) = cvtpk(v, vn);
;             }
;         }
.LBB0_823:
	s_lshl_b32 s4, s73, 8
	s_lshl_b32 s62, s74, 6
	s_add_i32 s62, s62, s4
	v_lshl_or_b32 v130, v145, 2, s62
	s_lshl_b32 s3, s3, 5
	s_or_b32 s2, s3, s2
	v_ashrrev_i32_e32 v131, 31, v130
	v_or_b32_e32 v132, s2, v144
	v_lshlrev_b64 v[130:131], 13, v[130:131]
	v_lshl_add_u64 v[130:131], s[18:19], 0, v[130:131]
	v_ashrrev_i32_e32 v133, 31, v132
	v_and_b32_e32 v128, 1, v143
	v_lshl_add_u64 v[130:131], v[132:133], 1, v[130:131]
	v_cmp_eq_u32_e64 s[2:3], 0, v128
	s_mov_b32 vcc_lo, 0x55555555
	s_mov_b32 vcc_hi, 0x55555555
	v_cndmask_b32_e64 v128, 30, 0, vcc
	v_add_co_u32_e64 v132, s[2:3], v128, v130
	s_mov_b32 s62, 0x2000
	s_nop 1
	v_addc_co_u32_e64 v133, s[2:3], 0, v131, s[2:3]
	v_cndmask_b32_dpp v128, v116, v124, vcc quad_perm:[1,0,3,2] row_mask:0xf bank_mask:0xf
	v_mov_b32_dpp v130, v124 quad_perm:[1,0,3,2] row_mask:0xf bank_mask:0xf bound_ctrl:1
	v_cndmask_b32_e32 v130, v116, v130, vcc
	v_cvt_pk_bf16_f32 v128, v128, v130
	global_store_dword v[132:133], v128, off
	v_cndmask_b32_dpp v131, v112, v120, vcc quad_perm:[1,0,3,2] row_mask:0xf bank_mask:0xf
	v_mov_b32_dpp v124, v120 quad_perm:[1,0,3,2] row_mask:0xf bank_mask:0xf bound_ctrl:1
	v_cndmask_b32_e32 v124, v112, v124, vcc
	v_cvt_pk_bf16_f32 v131, v131, v124
	global_store_dword v[132:133], v131, off offset:256
	v_add_co_u32_e64 v132, s[2:3], s62, v132
	v_cndmask_b32_dpp v116, v117, v125, vcc quad_perm:[1,0,3,2] row_mask:0xf bank_mask:0xf
	v_mov_b32_dpp v128, v125 quad_perm:[1,0,3,2] row_mask:0xf bank_mask:0xf bound_ctrl:1
	v_cndmask_b32_e32 v128, v117, v128, vcc
	v_cvt_pk_bf16_f32 v116, v116, v128
	v_addc_co_u32_e64 v133, s[2:3], 0, v133, s[2:3]
	global_store_dword v[132:133], v116, off
	v_cndmask_b32_dpp v130, v113, v121, vcc quad_perm:[1,0,3,2] row_mask:0xf bank_mask:0xf
	v_mov_b32_dpp v120, v121 quad_perm:[1,0,3,2] row_mask:0xf bank_mask:0xf bound_ctrl:1
	v_cndmask_b32_e32 v120, v113, v120, vcc
	v_cvt_pk_bf16_f32 v130, v130, v120
	global_store_dword v[132:133], v130, off offset:256
	v_add_co_u32_e64 v132, s[2:3], s62, v132
	v_cndmask_b32_dpp v112, v118, v126, vcc quad_perm:[1,0,3,2] row_mask:0xf bank_mask:0xf
	v_mov_b32_dpp v131, v126 quad_perm:[1,0,3,2] row_mask:0xf bank_mask:0xf bound_ctrl:1
	v_cndmask_b32_e32 v131, v118, v131, vcc
	v_cvt_pk_bf16_f32 v112, v112, v131
	v_addc_co_u32_e64 v133, s[2:3], 0, v133, s[2:3]
	global_store_dword v[132:133], v112, off
	v_cndmask_b32_dpp v124, v114, v122, vcc quad_perm:[1,0,3,2] row_mask:0xf bank_mask:0xf
	v_mov_b32_dpp v125, v122 quad_perm:[1,0,3,2] row_mask:0xf bank_mask:0xf bound_ctrl:1
	v_cndmask_b32_e32 v125, v114, v125, vcc
	v_cvt_pk_bf16_f32 v124, v124, v125
	global_store_dword v[132:133], v124, off offset:256
	v_add_co_u32_e64 v132, s[2:3], s62, v132
	v_cndmask_b32_dpp v117, v119, v127, vcc quad_perm:[1,0,3,2] row_mask:0xf bank_mask:0xf
	v_mov_b32_dpp v116, v127 quad_perm:[1,0,3,2] row_mask:0xf bank_mask:0xf bound_ctrl:1
	v_cndmask_b32_e32 v116, v119, v116, vcc
	v_cvt_pk_bf16_f32 v117, v117, v116
	v_addc_co_u32_e64 v133, s[2:3], 0, v133, s[2:3]
	global_store_dword v[132:133], v117, off
	v_cndmask_b32_dpp v128, v115, v123, vcc quad_perm:[1,0,3,2] row_mask:0xf bank_mask:0xf
	v_mov_b32_dpp v121, v123 quad_perm:[1,0,3,2] row_mask:0xf bank_mask:0xf bound_ctrl:1
	v_cndmask_b32_e32 v121, v115, v121, vcc
	v_cvt_pk_bf16_f32 v128, v128, v121
	global_store_dword v[132:133], v128, off offset:256
	s_mov_b32 s62, 0x1a000
	v_add_co_u32_e64 v132, s[2:3], s62, v132
	v_cndmask_b32_dpp v113, v100, v108, vcc quad_perm:[1,0,3,2] row_mask:0xf bank_mask:0xf
	v_mov_b32_dpp v130, v108 quad_perm:[1,0,3,2] row_mask:0xf bank_mask:0xf bound_ctrl:1
	v_cndmask_b32_e32 v130, v100, v130, vcc
	v_cvt_pk_bf16_f32 v113, v113, v130
	v_addc_co_u32_e64 v133, s[2:3], 0, v133, s[2:3]
	global_store_dword v[132:133], v113, off
	v_cndmask_b32_dpp v120, v96, v104, vcc quad_perm:[1,0,3,2] row_mask:0xf bank_mask:0xf
	v_mov_b32_dpp v126, v104 quad_perm:[1,0,3,2] row_mask:0xf bank_mask:0xf bound_ctrl:1
	v_cndmask_b32_e32 v126, v96, v126, vcc
	v_cvt_pk_bf16_f32 v120, v120, v126
	global_store_dword v[132:133], v120, off offset:256
	s_mov_b32 s62, 0x2000
	v_add_co_u32_e64 v132, s[2:3], s62, v132
	v_cndmask_b32_dpp v118, v101, v109, vcc quad_perm:[1,0,3,2] row_mask:0xf bank_mask:0xf
	v_mov_b32_dpp v112, v109 quad_perm:[1,0,3,2] row_mask:0xf bank_mask:0xf bound_ctrl:1
	v_cndmask_b32_e32 v112, v101, v112, vcc
	v_cvt_pk_bf16_f32 v118, v118, v112
	v_addc_co_u32_e64 v133, s[2:3], 0, v133, s[2:3]
	global_store_dword v[132:133], v118, off
	v_cndmask_b32_dpp v131, v97, v105, vcc quad_perm:[1,0,3,2] row_mask:0xf bank_mask:0xf
	v_mov_b32_dpp v122, v105 quad_perm:[1,0,3,2] row_mask:0xf bank_mask:0xf bound_ctrl:1
	v_cndmask_b32_e32 v122, v97, v122, vcc
	v_cvt_pk_bf16_f32 v131, v131, v122
	global_store_dword v[132:133], v131, off offset:256
	v_add_co_u32_e64 v132, s[2:3], s62, v132
	v_cndmask_b32_dpp v114, v102, v110, vcc quad_perm:[1,0,3,2] row_mask:0xf bank_mask:0xf
	v_mov_b32_dpp v124, v110 quad_perm:[1,0,3,2] row_mask:0xf bank_mask:0xf bound_ctrl:1
	v_cndmask_b32_e32 v124, v102, v124, vcc
	v_cvt_pk_bf16_f32 v114, v114, v124
	v_addc_co_u32_e64 v133, s[2:3], 0, v133, s[2:3]
	global_store_dword v[132:133], v114, off
	v_cndmask_b32_dpp v125, v98, v106, vcc quad_perm:[1,0,3,2] row_mask:0xf bank_mask:0xf
	v_mov_b32_dpp v127, v106 quad_perm:[1,0,3,2] row_mask:0xf bank_mask:0xf bound_ctrl:1
	v_cndmask_b32_e32 v127, v98, v127, vcc
	v_cvt_pk_bf16_f32 v125, v125, v127
	global_store_dword v[132:133], v125, off offset:256
	v_add_co_u32_e64 v132, s[2:3], s62, v132
	v_cndmask_b32_dpp v119, v103, v111, vcc quad_perm:[1,0,3,2] row_mask:0xf bank_mask:0xf
	v_mov_b32_dpp v117, v111 quad_perm:[1,0,3,2] row_mask:0xf bank_mask:0xf bound_ctrl:1
; __device__ __forceinline__ float xor1f(float v) { return __int_as_float(__builtin_amdgcn_update_dpp(0, __float_as_int(v), 0xB1, 0xF, 0xF, true)); }
; template <int K, int EPI>
; __device__ __forceinline__ void gemm_tile(const u16* __restrict__ A, const u16* __restrict__ Bt, int brow, int bcol,
;                                           u16* Cb, int ldc, const float* R, float* Cf) {
;     ...
;   const int row0 = brow + wr * 64 + fq * 4, col0 = bcol + wc * 32 + fr;
;   if constexpr (EPI == 0) {
;     u16* cb = Cb + (size_t)row0 * ldc + col0;
; #pragma unroll
;     for (int ai = 0; ai < 2; ++ai)
; #pragma unroll
;       for (int m = 0; m < 4; ++m)
; #pragma unroll
;         for (int j = 0; j < 4; ++j) {
;           u16* cr = cb + (size_t)(ai * HALF + m * 16 + j) * ldc;
; #pragma unroll
;           for (int bj = 0; bj < 2; ++bj)
; #pragma unroll
;             for (int n = 0; n < 2; ++n) {
;               const float v = acc[ai][bj][m][n][j];
;               const float vn = xor1f(v);
;               if ((fr & 1) == 0) *(unsigned*)(cr + bj * HALF + n * 16) = cvtpk(v, vn);
;             }
;         }
	v_cndmask_b32_e32 v117, v103, v117, vcc
	v_cvt_pk_bf16_f32 v119, v119, v117
	v_addc_co_u32_e64 v133, s[2:3], 0, v133, s[2:3]
	global_store_dword v[132:133], v119, off
	v_cndmask_b32_dpp v116, v99, v107, vcc quad_perm:[1,0,3,2] row_mask:0xf bank_mask:0xf
	v_mov_b32_dpp v123, v107 quad_perm:[1,0,3,2] row_mask:0xf bank_mask:0xf bound_ctrl:1
	v_cndmask_b32_e32 v123, v99, v123, vcc
	v_cvt_pk_bf16_f32 v116, v116, v123
	global_store_dword v[132:133], v116, off offset:256
	s_mov_b32 s62, 0x1a000
	v_add_co_u32_e64 v132, s[2:3], s62, v132
	v_cndmask_b32_dpp v115, v84, v92, vcc quad_perm:[1,0,3,2] row_mask:0xf bank_mask:0xf
	v_mov_b32_dpp v128, v92 quad_perm:[1,0,3,2] row_mask:0xf bank_mask:0xf bound_ctrl:1
	v_cndmask_b32_e32 v128, v84, v128, vcc
	v_cvt_pk_bf16_f32 v115, v115, v128
	v_addc_co_u32_e64 v133, s[2:3], 0, v133, s[2:3]
	global_store_dword v[132:133], v115, off
	v_cndmask_b32_dpp v121, v80, v88, vcc quad_perm:[1,0,3,2] row_mask:0xf bank_mask:0xf
	v_mov_b32_dpp v108, v88 quad_perm:[1,0,3,2] row_mask:0xf bank_mask:0xf bound_ctrl:1
	v_cndmask_b32_e32 v108, v80, v108, vcc
	v_cvt_pk_bf16_f32 v121, v121, v108
	global_store_dword v[132:133], v121, off offset:256
	s_mov_b32 s62, 0x2000
	v_add_co_u32_e64 v132, s[2:3], s62, v132
	v_cndmask_b32_dpp v100, v85, v93, vcc quad_perm:[1,0,3,2] row_mask:0xf bank_mask:0xf
	v_mov_b32_dpp v113, v93 quad_perm:[1,0,3,2] row_mask:0xf bank_mask:0xf bound_ctrl:1
	v_cndmask_b32_e32 v113, v85, v113, vcc
	v_cvt_pk_bf16_f32 v100, v100, v113
	v_addc_co_u32_e64 v133, s[2:3], 0, v133, s[2:3]
	global_store_dword v[132:133], v100, off
	v_cndmask_b32_dpp v130, v81, v89, vcc quad_perm:[1,0,3,2] row_mask:0xf bank_mask:0xf
	v_mov_b32_dpp v104, v89 quad_perm:[1,0,3,2] row_mask:0xf bank_mask:0xf bound_ctrl:1
	v_cndmask_b32_e32 v104, v81, v104, vcc
	v_cvt_pk_bf16_f32 v130, v130, v104
	global_store_dword v[132:133], v130, off offset:256
	v_add_co_u32_e64 v132, s[2:3], s62, v132
	v_cndmask_b32_dpp v96, v86, v94, vcc quad_perm:[1,0,3,2] row_mask:0xf bank_mask:0xf
	v_mov_b32_dpp v120, v94 quad_perm:[1,0,3,2] row_mask:0xf bank_mask:0xf bound_ctrl:1
	v_cndmask_b32_e32 v120, v86, v120, vcc
	v_cvt_pk_bf16_f32 v96, v96, v120
	v_addc_co_u32_e64 v133, s[2:3], 0, v133, s[2:3]
	global_store_dword v[132:133], v96, off
	v_cndmask_b32_dpp v126, v82, v90, vcc quad_perm:[1,0,3,2] row_mask:0xf bank_mask:0xf
	v_mov_b32_dpp v109, v90 quad_perm:[1,0,3,2] row_mask:0xf bank_mask:0xf bound_ctrl:1
	v_cndmask_b32_e32 v109, v82, v109, vcc
	v_cvt_pk_bf16_f32 v126, v126, v109
	global_store_dword v[132:133], v126, off offset:256
	v_add_co_u32_e64 v132, s[2:3], s62, v132
	v_cndmask_b32_dpp v101, v87, v95, vcc quad_perm:[1,0,3,2] row_mask:0xf bank_mask:0xf
	v_mov_b32_dpp v118, v95 quad_perm:[1,0,3,2] row_mask:0xf bank_mask:0xf bound_ctrl:1
	v_cndmask_b32_e32 v118, v87, v118, vcc
	v_cvt_pk_bf16_f32 v101, v101, v118
	v_addc_co_u32_e64 v133, s[2:3], 0, v133, s[2:3]
	global_store_dword v[132:133], v101, off
	v_cndmask_b32_dpp v112, v83, v91, vcc quad_perm:[1,0,3,2] row_mask:0xf bank_mask:0xf
	v_mov_b32_dpp v105, v91 quad_perm:[1,0,3,2] row_mask:0xf bank_mask:0xf bound_ctrl:1
	v_cndmask_b32_e32 v105, v83, v105, vcc
	v_cvt_pk_bf16_f32 v112, v112, v105
	global_store_dword v[132:133], v112, off offset:256
	s_mov_b32 s62, 0x1a000
	v_add_co_u32_e64 v132, s[2:3], s62, v132
	v_cndmask_b32_dpp v97, v68, v76, vcc quad_perm:[1,0,3,2] row_mask:0xf bank_mask:0xf
	v_mov_b32_dpp v131, v76 quad_perm:[1,0,3,2] row_mask:0xf bank_mask:0xf bound_ctrl:1
	v_cndmask_b32_e32 v131, v68, v131, vcc
	v_cvt_pk_bf16_f32 v97, v97, v131
	v_addc_co_u32_e64 v133, s[2:3], 0, v133, s[2:3]
	global_store_dword v[132:133], v97, off
	v_cndmask_b32_dpp v122, v64, v72, vcc quad_perm:[1,0,3,2] row_mask:0xf bank_mask:0xf
	v_mov_b32_dpp v110, v72 quad_perm:[1,0,3,2] row_mask:0xf bank_mask:0xf bound_ctrl:1
	v_cndmask_b32_e32 v110, v64, v110, vcc
	v_cvt_pk_bf16_f32 v122, v122, v110
	global_store_dword v[132:133], v122, off offset:256
	s_mov_b32 s62, 0x2000
	v_add_co_u32_e64 v132, s[2:3], s62, v132
	v_cndmask_b32_dpp v102, v69, v77, vcc quad_perm:[1,0,3,2] row_mask:0xf bank_mask:0xf
	v_mov_b32_dpp v114, v77 quad_perm:[1,0,3,2] row_mask:0xf bank_mask:0xf bound_ctrl:1
	v_cndmask_b32_e32 v114, v69, v114, vcc
	v_cvt_pk_bf16_f32 v102, v102, v114
	v_addc_co_u32_e64 v133, s[2:3], 0, v133, s[2:3]
	global_store_dword v[132:133], v102, off
	v_cndmask_b32_dpp v124, v65, v73, vcc quad_perm:[1,0,3,2] row_mask:0xf bank_mask:0xf
	v_mov_b32_dpp v106, v73 quad_perm:[1,0,3,2] row_mask:0xf bank_mask:0xf bound_ctrl:1
	v_cndmask_b32_e32 v106, v65, v106, vcc
	v_cvt_pk_bf16_f32 v124, v124, v106
	global_store_dword v[132:133], v124, off offset:256
	v_add_co_u32_e64 v132, s[2:3], s62, v132
	v_cndmask_b32_dpp v98, v70, v78, vcc quad_perm:[1,0,3,2] row_mask:0xf bank_mask:0xf
	v_mov_b32_dpp v125, v78 quad_perm:[1,0,3,2] row_mask:0xf bank_mask:0xf bound_ctrl:1
	v_cndmask_b32_e32 v125, v70, v125, vcc
	v_cvt_pk_bf16_f32 v98, v98, v125
	v_addc_co_u32_e64 v133, s[2:3], 0, v133, s[2:3]
	global_store_dword v[132:133], v98, off
	v_cndmask_b32_dpp v127, v66, v74, vcc quad_perm:[1,0,3,2] row_mask:0xf bank_mask:0xf
	v_mov_b32_dpp v111, v74 quad_perm:[1,0,3,2] row_mask:0xf bank_mask:0xf bound_ctrl:1
	v_cndmask_b32_e32 v111, v66, v111, vcc
	v_cvt_pk_bf16_f32 v127, v127, v111
	global_store_dword v[132:133], v127, off offset:256
	v_add_co_u32_e64 v132, s[2:3], s62, v132
	v_cndmask_b32_dpp v103, v71, v79, vcc quad_perm:[1,0,3,2] row_mask:0xf bank_mask:0xf
	v_mov_b32_dpp v119, v79 quad_perm:[1,0,3,2] row_mask:0xf bank_mask:0xf bound_ctrl:1
	v_cndmask_b32_e32 v119, v71, v119, vcc
	v_cvt_pk_bf16_f32 v103, v103, v119
	v_addc_co_u32_e64 v133, s[2:3], 0, v133, s[2:3]
; __device__ __forceinline__ float xor1f(float v) { return __int_as_float(__builtin_amdgcn_update_dpp(0, __float_as_int(v), 0xB1, 0xF, 0xF, true)); }
; template <int K, int EPI>
; __device__ __forceinline__ void gemm_tile(const u16* __restrict__ A, const u16* __restrict__ Bt, int brow, int bcol,
;                                           u16* Cb, int ldc, const float* R, float* Cf) {
;     ...
;   const int row0 = brow + wr * 64 + fq * 4, col0 = bcol + wc * 32 + fr;
;   if constexpr (EPI == 0) {
;     u16* cb = Cb + (size_t)row0 * ldc + col0;
; #pragma unroll
;     for (int ai = 0; ai < 2; ++ai)
; #pragma unroll
;       for (int m = 0; m < 4; ++m)
; #pragma unroll
;         for (int j = 0; j < 4; ++j) {
;           u16* cr = cb + (size_t)(ai * HALF + m * 16 + j) * ldc;
; #pragma unroll
;           for (int bj = 0; bj < 2; ++bj)
; #pragma unroll
;             for (int n = 0; n < 2; ++n) {
;               const float v = acc[ai][bj][m][n][j];
;               const float vn = xor1f(v);
;               if ((fr & 1) == 0) *(unsigned*)(cr + bj * HALF + n * 16) = cvtpk(v, vn);
;             }
;         }
	global_store_dword v[132:133], v103, off
	v_cndmask_b32_dpp v117, v67, v75, vcc quad_perm:[1,0,3,2] row_mask:0xf bank_mask:0xf
	v_mov_b32_dpp v107, v75 quad_perm:[1,0,3,2] row_mask:0xf bank_mask:0xf bound_ctrl:1
	v_cndmask_b32_e32 v107, v67, v107, vcc
	v_cvt_pk_bf16_f32 v117, v117, v107
	global_store_dword v[132:133], v117, off offset:256
	s_mov_b32 s62, 0x9a000
	v_add_co_u32_e64 v132, s[2:3], s62, v132
	v_cndmask_b32_dpp v99, v56, v60, vcc quad_perm:[1,0,3,2] row_mask:0xf bank_mask:0xf
	v_mov_b32_dpp v116, v60 quad_perm:[1,0,3,2] row_mask:0xf bank_mask:0xf bound_ctrl:1
	v_cndmask_b32_e32 v116, v56, v116, vcc
	v_cvt_pk_bf16_f32 v99, v99, v116
	v_addc_co_u32_e64 v133, s[2:3], 0, v133, s[2:3]
	global_store_dword v[132:133], v99, off
	v_cndmask_b32_dpp v123, v48, v52, vcc quad_perm:[1,0,3,2] row_mask:0xf bank_mask:0xf
	v_mov_b32_dpp v92, v52 quad_perm:[1,0,3,2] row_mask:0xf bank_mask:0xf bound_ctrl:1
	v_cndmask_b32_e32 v92, v48, v92, vcc
	v_cvt_pk_bf16_f32 v123, v123, v92
	global_store_dword v[132:133], v123, off offset:256
	s_mov_b32 s62, 0x2000
	v_add_co_u32_e64 v132, s[2:3], s62, v132
	v_cndmask_b32_dpp v84, v57, v61, vcc quad_perm:[1,0,3,2] row_mask:0xf bank_mask:0xf
	v_mov_b32_dpp v115, v61 quad_perm:[1,0,3,2] row_mask:0xf bank_mask:0xf bound_ctrl:1
	v_cndmask_b32_e32 v115, v57, v115, vcc
	v_cvt_pk_bf16_f32 v84, v84, v115
	v_addc_co_u32_e64 v133, s[2:3], 0, v133, s[2:3]
	global_store_dword v[132:133], v84, off
	v_cndmask_b32_dpp v128, v49, v53, vcc quad_perm:[1,0,3,2] row_mask:0xf bank_mask:0xf
	v_mov_b32_dpp v88, v53 quad_perm:[1,0,3,2] row_mask:0xf bank_mask:0xf bound_ctrl:1
	v_cndmask_b32_e32 v88, v49, v88, vcc
	v_cvt_pk_bf16_f32 v128, v128, v88
	global_store_dword v[132:133], v128, off offset:256
	v_add_co_u32_e64 v132, s[2:3], s62, v132
	v_cndmask_b32_dpp v80, v58, v62, vcc quad_perm:[1,0,3,2] row_mask:0xf bank_mask:0xf
	v_mov_b32_dpp v121, v62 quad_perm:[1,0,3,2] row_mask:0xf bank_mask:0xf bound_ctrl:1
	v_cndmask_b32_e32 v121, v58, v121, vcc
	v_cvt_pk_bf16_f32 v80, v80, v121
	v_addc_co_u32_e64 v133, s[2:3], 0, v133, s[2:3]
	global_store_dword v[132:133], v80, off
	v_cndmask_b32_dpp v108, v50, v54, vcc quad_perm:[1,0,3,2] row_mask:0xf bank_mask:0xf
	v_mov_b32_dpp v93, v54 quad_perm:[1,0,3,2] row_mask:0xf bank_mask:0xf bound_ctrl:1
	v_cndmask_b32_e32 v93, v50, v93, vcc
	v_cvt_pk_bf16_f32 v108, v108, v93
	global_store_dword v[132:133], v108, off offset:256
	v_add_co_u32_e64 v132, s[2:3], s62, v132
	v_cndmask_b32_dpp v85, v59, v63, vcc quad_perm:[1,0,3,2] row_mask:0xf bank_mask:0xf
	v_mov_b32_dpp v100, v63 quad_perm:[1,0,3,2] row_mask:0xf bank_mask:0xf bound_ctrl:1
	v_cndmask_b32_e32 v100, v59, v100, vcc
	v_cvt_pk_bf16_f32 v85, v85, v100
	v_addc_co_u32_e64 v133, s[2:3], 0, v133, s[2:3]
	global_store_dword v[132:133], v85, off
	v_cndmask_b32_dpp v113, v51, v55, vcc quad_perm:[1,0,3,2] row_mask:0xf bank_mask:0xf
	v_mov_b32_dpp v89, v55 quad_perm:[1,0,3,2] row_mask:0xf bank_mask:0xf bound_ctrl:1
	v_cndmask_b32_e32 v89, v51, v89, vcc
	v_cvt_pk_bf16_f32 v113, v113, v89
	global_store_dword v[132:133], v113, off offset:256
	s_mov_b32 s62, 0x1a000
	v_add_co_u32_e64 v132, s[2:3], s62, v132
	v_cndmask_b32_dpp v81, v40, v44, vcc quad_perm:[1,0,3,2] row_mask:0xf bank_mask:0xf
	v_mov_b32_dpp v130, v44 quad_perm:[1,0,3,2] row_mask:0xf bank_mask:0xf bound_ctrl:1
	v_cndmask_b32_e32 v130, v40, v130, vcc
	v_cvt_pk_bf16_f32 v81, v81, v130
	v_addc_co_u32_e64 v133, s[2:3], 0, v133, s[2:3]
	global_store_dword v[132:133], v81, off
	v_cndmask_b32_dpp v104, v32, v36, vcc quad_perm:[1,0,3,2] row_mask:0xf bank_mask:0xf
	v_mov_b32_dpp v94, v36 quad_perm:[1,0,3,2] row_mask:0xf bank_mask:0xf bound_ctrl:1
	v_cndmask_b32_e32 v94, v32, v94, vcc
	v_cvt_pk_bf16_f32 v104, v104, v94
	global_store_dword v[132:133], v104, off offset:256
	s_mov_b32 s62, 0x2000
	v_add_co_u32_e64 v132, s[2:3], s62, v132
	v_cndmask_b32_dpp v86, v41, v45, vcc quad_perm:[1,0,3,2] row_mask:0xf bank_mask:0xf
	v_mov_b32_dpp v96, v45 quad_perm:[1,0,3,2] row_mask:0xf bank_mask:0xf bound_ctrl:1
	v_cndmask_b32_e32 v96, v41, v96, vcc
	v_cvt_pk_bf16_f32 v86, v86, v96
	v_addc_co_u32_e64 v133, s[2:3], 0, v133, s[2:3]
	global_store_dword v[132:133], v86, off
	v_cndmask_b32_dpp v120, v33, v37, vcc quad_perm:[1,0,3,2] row_mask:0xf bank_mask:0xf
	v_mov_b32_dpp v90, v37 quad_perm:[1,0,3,2] row_mask:0xf bank_mask:0xf bound_ctrl:1
	v_cndmask_b32_e32 v90, v33, v90, vcc
	v_cvt_pk_bf16_f32 v120, v120, v90
	global_store_dword v[132:133], v120, off offset:256
	v_add_co_u32_e64 v132, s[2:3], s62, v132
	v_cndmask_b32_dpp v82, v42, v46, vcc quad_perm:[1,0,3,2] row_mask:0xf bank_mask:0xf
	v_mov_b32_dpp v126, v46 quad_perm:[1,0,3,2] row_mask:0xf bank_mask:0xf bound_ctrl:1
	v_cndmask_b32_e32 v126, v42, v126, vcc
	v_cvt_pk_bf16_f32 v82, v82, v126
	v_addc_co_u32_e64 v133, s[2:3], 0, v133, s[2:3]
	global_store_dword v[132:133], v82, off
	v_cndmask_b32_dpp v109, v34, v38, vcc quad_perm:[1,0,3,2] row_mask:0xf bank_mask:0xf
	v_mov_b32_dpp v95, v38 quad_perm:[1,0,3,2] row_mask:0xf bank_mask:0xf bound_ctrl:1
	v_cndmask_b32_e32 v95, v34, v95, vcc
	v_cvt_pk_bf16_f32 v109, v109, v95
	global_store_dword v[132:133], v109, off offset:256
	v_add_co_u32_e64 v132, s[2:3], s62, v132
	v_cndmask_b32_dpp v87, v43, v47, vcc quad_perm:[1,0,3,2] row_mask:0xf bank_mask:0xf
	v_mov_b32_dpp v101, v47 quad_perm:[1,0,3,2] row_mask:0xf bank_mask:0xf bound_ctrl:1
	v_cndmask_b32_e32 v101, v43, v101, vcc
	v_cvt_pk_bf16_f32 v87, v87, v101
	v_addc_co_u32_e64 v133, s[2:3], 0, v133, s[2:3]
	global_store_dword v[132:133], v87, off
	v_cndmask_b32_dpp v118, v35, v39, vcc quad_perm:[1,0,3,2] row_mask:0xf bank_mask:0xf
; __device__ __forceinline__ float xor1f(float v) { return __int_as_float(__builtin_amdgcn_update_dpp(0, __float_as_int(v), 0xB1, 0xF, 0xF, true)); }
; template <int K, int EPI>
; __device__ __forceinline__ void gemm_tile(const u16* __restrict__ A, const u16* __restrict__ Bt, int brow, int bcol,
;                                           u16* Cb, int ldc, const float* R, float* Cf) {
;     ...
;   const int row0 = brow + wr * 64 + fq * 4, col0 = bcol + wc * 32 + fr;
;   if constexpr (EPI == 0) {
;     u16* cb = Cb + (size_t)row0 * ldc + col0;
; #pragma unroll
;     for (int ai = 0; ai < 2; ++ai)
; #pragma unroll
;       for (int m = 0; m < 4; ++m)
; #pragma unroll
;         for (int j = 0; j < 4; ++j) {
;           u16* cr = cb + (size_t)(ai * HALF + m * 16 + j) * ldc;
; #pragma unroll
;           for (int bj = 0; bj < 2; ++bj)
; #pragma unroll
;             for (int n = 0; n < 2; ++n) {
;               const float v = acc[ai][bj][m][n][j];
;               const float vn = xor1f(v);
;               if ((fr & 1) == 0) *(unsigned*)(cr + bj * HALF + n * 16) = cvtpk(v, vn);
;             }
;         }
	v_mov_b32_dpp v91, v39 quad_perm:[1,0,3,2] row_mask:0xf bank_mask:0xf bound_ctrl:1
	v_cndmask_b32_e32 v91, v35, v91, vcc
	v_cvt_pk_bf16_f32 v118, v118, v91
	global_store_dword v[132:133], v118, off offset:256
	s_mov_b32 s62, 0x1a000
	v_add_co_u32_e64 v132, s[2:3], s62, v132
	v_cndmask_b32_dpp v83, v24, v28, vcc quad_perm:[1,0,3,2] row_mask:0xf bank_mask:0xf
	v_mov_b32_dpp v112, v28 quad_perm:[1,0,3,2] row_mask:0xf bank_mask:0xf bound_ctrl:1
	v_cndmask_b32_e32 v112, v24, v112, vcc
	v_cvt_pk_bf16_f32 v83, v83, v112
	v_addc_co_u32_e64 v133, s[2:3], 0, v133, s[2:3]
	global_store_dword v[132:133], v83, off
	v_cndmask_b32_dpp v105, v16, v20, vcc quad_perm:[1,0,3,2] row_mask:0xf bank_mask:0xf
	v_mov_b32_dpp v76, v20 quad_perm:[1,0,3,2] row_mask:0xf bank_mask:0xf bound_ctrl:1
	v_cndmask_b32_e32 v76, v16, v76, vcc
	v_cvt_pk_bf16_f32 v105, v105, v76
	global_store_dword v[132:133], v105, off offset:256
	s_mov_b32 s62, 0x2000
	v_add_co_u32_e64 v132, s[2:3], s62, v132
	v_cndmask_b32_dpp v68, v25, v29, vcc quad_perm:[1,0,3,2] row_mask:0xf bank_mask:0xf
	v_mov_b32_dpp v97, v29 quad_perm:[1,0,3,2] row_mask:0xf bank_mask:0xf bound_ctrl:1
	v_cndmask_b32_e32 v97, v25, v97, vcc
	v_cvt_pk_bf16_f32 v68, v68, v97
	v_addc_co_u32_e64 v133, s[2:3], 0, v133, s[2:3]
	global_store_dword v[132:133], v68, off
	v_cndmask_b32_dpp v131, v17, v21, vcc quad_perm:[1,0,3,2] row_mask:0xf bank_mask:0xf
	v_mov_b32_dpp v72, v21 quad_perm:[1,0,3,2] row_mask:0xf bank_mask:0xf bound_ctrl:1
	v_cndmask_b32_e32 v72, v17, v72, vcc
	v_cvt_pk_bf16_f32 v131, v131, v72
	global_store_dword v[132:133], v131, off offset:256
	v_add_co_u32_e64 v132, s[2:3], s62, v132
	v_cndmask_b32_dpp v64, v26, v30, vcc quad_perm:[1,0,3,2] row_mask:0xf bank_mask:0xf
	v_mov_b32_dpp v122, v30 quad_perm:[1,0,3,2] row_mask:0xf bank_mask:0xf bound_ctrl:1
	v_cndmask_b32_e32 v122, v26, v122, vcc
	v_cvt_pk_bf16_f32 v64, v64, v122
	v_addc_co_u32_e64 v133, s[2:3], 0, v133, s[2:3]
	global_store_dword v[132:133], v64, off
	v_cndmask_b32_dpp v110, v18, v22, vcc quad_perm:[1,0,3,2] row_mask:0xf bank_mask:0xf
	v_mov_b32_dpp v77, v22 quad_perm:[1,0,3,2] row_mask:0xf bank_mask:0xf bound_ctrl:1
	v_cndmask_b32_e32 v77, v18, v77, vcc
	v_cvt_pk_bf16_f32 v110, v110, v77
	global_store_dword v[132:133], v110, off offset:256
	v_add_co_u32_e64 v132, s[2:3], s62, v132
	v_cndmask_b32_dpp v69, v27, v31, vcc quad_perm:[1,0,3,2] row_mask:0xf bank_mask:0xf
	v_mov_b32_dpp v102, v31 quad_perm:[1,0,3,2] row_mask:0xf bank_mask:0xf bound_ctrl:1
	v_cndmask_b32_e32 v102, v27, v102, vcc
	v_cvt_pk_bf16_f32 v69, v69, v102
	v_addc_co_u32_e64 v133, s[2:3], 0, v133, s[2:3]
	global_store_dword v[132:133], v69, off
	v_cndmask_b32_dpp v114, v19, v23, vcc quad_perm:[1,0,3,2] row_mask:0xf bank_mask:0xf
	v_mov_b32_dpp v73, v23 quad_perm:[1,0,3,2] row_mask:0xf bank_mask:0xf bound_ctrl:1
	v_cndmask_b32_e32 v73, v19, v73, vcc
	v_cvt_pk_bf16_f32 v114, v114, v73
	global_store_dword v[132:133], v114, off offset:256
	s_mov_b32 s62, 0x1a000
	v_add_co_u32_e64 v132, s[2:3], s62, v132
	v_cndmask_b32_dpp v65, v8, v12, vcc quad_perm:[1,0,3,2] row_mask:0xf bank_mask:0xf
	v_mov_b32_dpp v124, v12 quad_perm:[1,0,3,2] row_mask:0xf bank_mask:0xf bound_ctrl:1
	v_cndmask_b32_e32 v124, v8, v124, vcc
	v_cvt_pk_bf16_f32 v65, v65, v124
	v_addc_co_u32_e64 v133, s[2:3], 0, v133, s[2:3]
	global_store_dword v[132:133], v65, off
	v_cndmask_b32_dpp v106, v0, v4, vcc quad_perm:[1,0,3,2] row_mask:0xf bank_mask:0xf
	v_mov_b32_dpp v78, v4 quad_perm:[1,0,3,2] row_mask:0xf bank_mask:0xf bound_ctrl:1
	v_cndmask_b32_e32 v78, v0, v78, vcc
	v_cvt_pk_bf16_f32 v106, v106, v78
	global_store_dword v[132:133], v106, off offset:256
	s_mov_b32 s62, 0x2000
	v_add_co_u32_e64 v132, s[2:3], s62, v132
	v_cndmask_b32_dpp v70, v9, v13, vcc quad_perm:[1,0,3,2] row_mask:0xf bank_mask:0xf
	v_mov_b32_dpp v98, v13 quad_perm:[1,0,3,2] row_mask:0xf bank_mask:0xf bound_ctrl:1
	v_cndmask_b32_e32 v98, v9, v98, vcc
	v_cvt_pk_bf16_f32 v70, v70, v98
	v_addc_co_u32_e64 v133, s[2:3], 0, v133, s[2:3]
	global_store_dword v[132:133], v70, off
	v_cndmask_b32_dpp v125, v1, v5, vcc quad_perm:[1,0,3,2] row_mask:0xf bank_mask:0xf
	v_mov_b32_dpp v74, v5 quad_perm:[1,0,3,2] row_mask:0xf bank_mask:0xf bound_ctrl:1
	v_cndmask_b32_e32 v74, v1, v74, vcc
	v_cvt_pk_bf16_f32 v125, v125, v74
	global_store_dword v[132:133], v125, off offset:256
	v_add_co_u32_e64 v132, s[2:3], s62, v132
	v_cndmask_b32_dpp v66, v10, v14, vcc quad_perm:[1,0,3,2] row_mask:0xf bank_mask:0xf
	v_mov_b32_dpp v127, v14 quad_perm:[1,0,3,2] row_mask:0xf bank_mask:0xf bound_ctrl:1
	v_cndmask_b32_e32 v127, v10, v127, vcc
	v_cvt_pk_bf16_f32 v66, v66, v127
	v_addc_co_u32_e64 v133, s[2:3], 0, v133, s[2:3]
	global_store_dword v[132:133], v66, off
	v_cndmask_b32_dpp v111, v2, v6, vcc quad_perm:[1,0,3,2] row_mask:0xf bank_mask:0xf
	v_mov_b32_dpp v79, v6 quad_perm:[1,0,3,2] row_mask:0xf bank_mask:0xf bound_ctrl:1
	v_cndmask_b32_e32 v79, v2, v79, vcc
	v_cvt_pk_bf16_f32 v111, v111, v79
	global_store_dword v[132:133], v111, off offset:256
	v_add_co_u32_e64 v132, s[2:3], s62, v132
	v_cndmask_b32_dpp v71, v11, v15, vcc quad_perm:[1,0,3,2] row_mask:0xf bank_mask:0xf
	v_mov_b32_dpp v103, v15 quad_perm:[1,0,3,2] row_mask:0xf bank_mask:0xf bound_ctrl:1
	v_cndmask_b32_e32 v103, v11, v103, vcc
	v_cvt_pk_bf16_f32 v71, v71, v103
	v_addc_co_u32_e64 v133, s[2:3], 0, v133, s[2:3]
	global_store_dword v[132:133], v71, off
	v_cndmask_b32_dpp v119, v3, v7, vcc quad_perm:[1,0,3,2] row_mask:0xf bank_mask:0xf
	v_mov_b32_dpp v75, v7 quad_perm:[1,0,3,2] row_mask:0xf bank_mask:0xf bound_ctrl:1
	v_cndmask_b32_e32 v75, v3, v75, vcc
	v_cvt_pk_bf16_f32 v119, v119, v75
	global_store_dword v[132:133], v119, off offset:256
	s_branch .LBB0_816

; __device__ __forceinline__ float xor1f(float v) { return __int_as_float(__builtin_amdgcn_update_dpp(0, __float_as_int(v), 0xB1, 0xF, 0xF, true)); }
; template <int K, int EPI>
; __device__ __forceinline__ void gemm_tile(const u16* __restrict__ A, const u16* __restrict__ Bt, int brow, int bcol,
;                                           u16* Cb, int ldc, const float* R, float* Cf) {
;     ...
;   const int row0 = brow + wr * 64 + fq * 4, col0 = bcol + wc * 32 + fr;
;   if constexpr (EPI == 0) {
;     u16* cb = Cb + (size_t)row0 * ldc + col0;
; #pragma unroll
;     for (int ai = 0; ai < 2; ++ai)
; #pragma unroll
;       for (int m = 0; m < 4; ++m)
; #pragma unroll
;         for (int j = 0; j < 4; ++j) {
;           u16* cr = cb + (size_t)(ai * HALF + m * 16 + j) * ldc;
; #pragma unroll
;           for (int bj = 0; bj < 2; ++bj)
; #pragma unroll
;             for (int n = 0; n < 2; ++n) {
;               const float v = acc[ai][bj][m][n][j];
;               const float vn = xor1f(v);
;               if ((fr & 1) == 0) *(unsigned*)(cr + bj * HALF + n * 16) = cvtpk(v, vn);
;             }
;         }
.LBB0_1617:
	s_lshl_b32 s2, s60, 8
	s_lshl_b32 s34, s61, 6
	s_add_i32 s34, s34, s2
	s_lshl_b32 s2, s5, 5
	s_or_b32 s2, s2, s4
	v_lshl_or_b32 v128, v143, 2, s34
	v_or_b32_e32 v130, s2, v142
	v_mov_b64_e32 v[132:133], s[42:43]
	v_mad_i64_i32 v[132:133], s[4:5], v128, s58, v[132:133]
	v_ashrrev_i32_e32 v131, 31, v130
	v_and_b32_e32 v128, 1, v141
	v_lshl_add_u64 v[130:131], v[130:131], 1, v[132:133]
	v_cmp_eq_u32_e64 s[4:5], 0, v128
	s_mov_b32 vcc_lo, 0x55555555
	s_mov_b32 vcc_hi, 0x55555555
	v_cndmask_b32_e64 v128, 30, 0, vcc
	v_add_co_u32_e64 v132, s[4:5], v128, v130
	s_mov_b32 s50, 0x6c00
	s_nop 1
	v_addc_co_u32_e64 v133, s[4:5], 0, v131, s[4:5]
	v_cndmask_b32_dpp v128, v116, v124, vcc quad_perm:[1,0,3,2] row_mask:0xf bank_mask:0xf
	v_mov_b32_dpp v130, v124 quad_perm:[1,0,3,2] row_mask:0xf bank_mask:0xf bound_ctrl:1
	v_cndmask_b32_e32 v130, v116, v130, vcc
	v_cvt_pk_bf16_f32 v128, v128, v130
	global_store_dword v[132:133], v128, off
	v_cndmask_b32_dpp v131, v112, v120, vcc quad_perm:[1,0,3,2] row_mask:0xf bank_mask:0xf
	v_mov_b32_dpp v124, v120 quad_perm:[1,0,3,2] row_mask:0xf bank_mask:0xf bound_ctrl:1
	v_cndmask_b32_e32 v124, v112, v124, vcc
	v_cvt_pk_bf16_f32 v131, v131, v124
	global_store_dword v[132:133], v131, off offset:256
	v_add_co_u32_e64 v132, s[4:5], s50, v132
	v_cndmask_b32_dpp v116, v117, v125, vcc quad_perm:[1,0,3,2] row_mask:0xf bank_mask:0xf
	v_mov_b32_dpp v128, v125 quad_perm:[1,0,3,2] row_mask:0xf bank_mask:0xf bound_ctrl:1
	v_cndmask_b32_e32 v128, v117, v128, vcc
	v_cvt_pk_bf16_f32 v116, v116, v128
	v_addc_co_u32_e64 v133, s[4:5], 0, v133, s[4:5]
	global_store_dword v[132:133], v116, off
	v_cndmask_b32_dpp v130, v113, v121, vcc quad_perm:[1,0,3,2] row_mask:0xf bank_mask:0xf
	v_mov_b32_dpp v120, v121 quad_perm:[1,0,3,2] row_mask:0xf bank_mask:0xf bound_ctrl:1
	v_cndmask_b32_e32 v120, v113, v120, vcc
	v_cvt_pk_bf16_f32 v130, v130, v120
	global_store_dword v[132:133], v130, off offset:256
	v_add_co_u32_e64 v132, s[4:5], s50, v132
	v_cndmask_b32_dpp v112, v118, v126, vcc quad_perm:[1,0,3,2] row_mask:0xf bank_mask:0xf
	v_mov_b32_dpp v131, v126 quad_perm:[1,0,3,2] row_mask:0xf bank_mask:0xf bound_ctrl:1
	v_cndmask_b32_e32 v131, v118, v131, vcc
	v_cvt_pk_bf16_f32 v112, v112, v131
	v_addc_co_u32_e64 v133, s[4:5], 0, v133, s[4:5]
	global_store_dword v[132:133], v112, off
	v_cndmask_b32_dpp v124, v114, v122, vcc quad_perm:[1,0,3,2] row_mask:0xf bank_mask:0xf
	v_mov_b32_dpp v125, v122 quad_perm:[1,0,3,2] row_mask:0xf bank_mask:0xf bound_ctrl:1
	v_cndmask_b32_e32 v125, v114, v125, vcc
	v_cvt_pk_bf16_f32 v124, v124, v125
	global_store_dword v[132:133], v124, off offset:256
	v_add_co_u32_e64 v132, s[4:5], s50, v132
	v_cndmask_b32_dpp v117, v119, v127, vcc quad_perm:[1,0,3,2] row_mask:0xf bank_mask:0xf
	v_mov_b32_dpp v116, v127 quad_perm:[1,0,3,2] row_mask:0xf bank_mask:0xf bound_ctrl:1
	v_cndmask_b32_e32 v116, v119, v116, vcc
	v_cvt_pk_bf16_f32 v117, v117, v116
	v_addc_co_u32_e64 v133, s[4:5], 0, v133, s[4:5]
	global_store_dword v[132:133], v117, off
	v_cndmask_b32_dpp v128, v115, v123, vcc quad_perm:[1,0,3,2] row_mask:0xf bank_mask:0xf
	v_mov_b32_dpp v121, v123 quad_perm:[1,0,3,2] row_mask:0xf bank_mask:0xf bound_ctrl:1
	v_cndmask_b32_e32 v121, v115, v121, vcc
	v_cvt_pk_bf16_f32 v128, v128, v121
	global_store_dword v[132:133], v128, off offset:256
	s_mov_b32 s50, 0x57c00
	v_add_co_u32_e64 v132, s[4:5], s50, v132
	v_cndmask_b32_dpp v113, v100, v108, vcc quad_perm:[1,0,3,2] row_mask:0xf bank_mask:0xf
	v_mov_b32_dpp v130, v108 quad_perm:[1,0,3,2] row_mask:0xf bank_mask:0xf bound_ctrl:1
	v_cndmask_b32_e32 v130, v100, v130, vcc
	v_cvt_pk_bf16_f32 v113, v113, v130
	v_addc_co_u32_e64 v133, s[4:5], 0, v133, s[4:5]
	global_store_dword v[132:133], v113, off
	v_cndmask_b32_dpp v120, v96, v104, vcc quad_perm:[1,0,3,2] row_mask:0xf bank_mask:0xf
	v_mov_b32_dpp v126, v104 quad_perm:[1,0,3,2] row_mask:0xf bank_mask:0xf bound_ctrl:1
	v_cndmask_b32_e32 v126, v96, v126, vcc
	v_cvt_pk_bf16_f32 v120, v120, v126
	global_store_dword v[132:133], v120, off offset:256
	s_mov_b32 s50, 0x6c00
	v_add_co_u32_e64 v132, s[4:5], s50, v132
	v_cndmask_b32_dpp v118, v101, v109, vcc quad_perm:[1,0,3,2] row_mask:0xf bank_mask:0xf
	v_mov_b32_dpp v112, v109 quad_perm:[1,0,3,2] row_mask:0xf bank_mask:0xf bound_ctrl:1
	v_cndmask_b32_e32 v112, v101, v112, vcc
	v_cvt_pk_bf16_f32 v118, v118, v112
	v_addc_co_u32_e64 v133, s[4:5], 0, v133, s[4:5]
	global_store_dword v[132:133], v118, off
	v_cndmask_b32_dpp v131, v97, v105, vcc quad_perm:[1,0,3,2] row_mask:0xf bank_mask:0xf
	v_mov_b32_dpp v122, v105 quad_perm:[1,0,3,2] row_mask:0xf bank_mask:0xf bound_ctrl:1
	v_cndmask_b32_e32 v122, v97, v122, vcc
	v_cvt_pk_bf16_f32 v131, v131, v122
	global_store_dword v[132:133], v131, off offset:256
	v_add_co_u32_e64 v132, s[4:5], s50, v132
	v_cndmask_b32_dpp v114, v102, v110, vcc quad_perm:[1,0,3,2] row_mask:0xf bank_mask:0xf
	v_mov_b32_dpp v124, v110 quad_perm:[1,0,3,2] row_mask:0xf bank_mask:0xf bound_ctrl:1
	v_cndmask_b32_e32 v124, v102, v124, vcc
	v_cvt_pk_bf16_f32 v114, v114, v124
	v_addc_co_u32_e64 v133, s[4:5], 0, v133, s[4:5]
	global_store_dword v[132:133], v114, off
	v_cndmask_b32_dpp v125, v98, v106, vcc quad_perm:[1,0,3,2] row_mask:0xf bank_mask:0xf
	v_mov_b32_dpp v127, v106 quad_perm:[1,0,3,2] row_mask:0xf bank_mask:0xf bound_ctrl:1
	v_cndmask_b32_e32 v127, v98, v127, vcc
	v_cvt_pk_bf16_f32 v125, v125, v127
	global_store_dword v[132:133], v125, off offset:256
	v_add_co_u32_e64 v132, s[4:5], s50, v132
	v_cndmask_b32_dpp v119, v103, v111, vcc quad_perm:[1,0,3,2] row_mask:0xf bank_mask:0xf
	v_mov_b32_dpp v117, v111 quad_perm:[1,0,3,2] row_mask:0xf bank_mask:0xf bound_ctrl:1
; __device__ __forceinline__ float xor1f(float v) { return __int_as_float(__builtin_amdgcn_update_dpp(0, __float_as_int(v), 0xB1, 0xF, 0xF, true)); }
; template <int K, int EPI>
; __device__ __forceinline__ void gemm_tile(const u16* __restrict__ A, const u16* __restrict__ Bt, int brow, int bcol,
;                                           u16* Cb, int ldc, const float* R, float* Cf) {
;     ...
;   const int row0 = brow + wr * 64 + fq * 4, col0 = bcol + wc * 32 + fr;
;   if constexpr (EPI == 0) {
;     u16* cb = Cb + (size_t)row0 * ldc + col0;
; #pragma unroll
;     for (int ai = 0; ai < 2; ++ai)
; #pragma unroll
;       for (int m = 0; m < 4; ++m)
; #pragma unroll
;         for (int j = 0; j < 4; ++j) {
;           u16* cr = cb + (size_t)(ai * HALF + m * 16 + j) * ldc;
; #pragma unroll
;           for (int bj = 0; bj < 2; ++bj)
; #pragma unroll
;             for (int n = 0; n < 2; ++n) {
;               const float v = acc[ai][bj][m][n][j];
;               const float vn = xor1f(v);
;               if ((fr & 1) == 0) *(unsigned*)(cr + bj * HALF + n * 16) = cvtpk(v, vn);
;             }
;         }
	v_cndmask_b32_e32 v117, v103, v117, vcc
	v_cvt_pk_bf16_f32 v119, v119, v117
	v_addc_co_u32_e64 v133, s[4:5], 0, v133, s[4:5]
	global_store_dword v[132:133], v119, off
	v_cndmask_b32_dpp v116, v99, v107, vcc quad_perm:[1,0,3,2] row_mask:0xf bank_mask:0xf
	v_mov_b32_dpp v123, v107 quad_perm:[1,0,3,2] row_mask:0xf bank_mask:0xf bound_ctrl:1
	v_cndmask_b32_e32 v123, v99, v123, vcc
	v_cvt_pk_bf16_f32 v116, v116, v123
	global_store_dword v[132:133], v116, off offset:256
	s_mov_b32 s50, 0x57c00
	v_add_co_u32_e64 v132, s[4:5], s50, v132
	v_cndmask_b32_dpp v115, v84, v92, vcc quad_perm:[1,0,3,2] row_mask:0xf bank_mask:0xf
	v_mov_b32_dpp v128, v92 quad_perm:[1,0,3,2] row_mask:0xf bank_mask:0xf bound_ctrl:1
	v_cndmask_b32_e32 v128, v84, v128, vcc
	v_cvt_pk_bf16_f32 v115, v115, v128
	v_addc_co_u32_e64 v133, s[4:5], 0, v133, s[4:5]
	global_store_dword v[132:133], v115, off
	v_cndmask_b32_dpp v121, v80, v88, vcc quad_perm:[1,0,3,2] row_mask:0xf bank_mask:0xf
	v_mov_b32_dpp v108, v88 quad_perm:[1,0,3,2] row_mask:0xf bank_mask:0xf bound_ctrl:1
	v_cndmask_b32_e32 v108, v80, v108, vcc
	v_cvt_pk_bf16_f32 v121, v121, v108
	global_store_dword v[132:133], v121, off offset:256
	s_mov_b32 s50, 0x6c00
	v_add_co_u32_e64 v132, s[4:5], s50, v132
	v_cndmask_b32_dpp v100, v85, v93, vcc quad_perm:[1,0,3,2] row_mask:0xf bank_mask:0xf
	v_mov_b32_dpp v113, v93 quad_perm:[1,0,3,2] row_mask:0xf bank_mask:0xf bound_ctrl:1
	v_cndmask_b32_e32 v113, v85, v113, vcc
	v_cvt_pk_bf16_f32 v100, v100, v113
	v_addc_co_u32_e64 v133, s[4:5], 0, v133, s[4:5]
	global_store_dword v[132:133], v100, off
	v_cndmask_b32_dpp v130, v81, v89, vcc quad_perm:[1,0,3,2] row_mask:0xf bank_mask:0xf
	v_mov_b32_dpp v104, v89 quad_perm:[1,0,3,2] row_mask:0xf bank_mask:0xf bound_ctrl:1
	v_cndmask_b32_e32 v104, v81, v104, vcc
	v_cvt_pk_bf16_f32 v130, v130, v104
	global_store_dword v[132:133], v130, off offset:256
	v_add_co_u32_e64 v132, s[4:5], s50, v132
	v_cndmask_b32_dpp v96, v86, v94, vcc quad_perm:[1,0,3,2] row_mask:0xf bank_mask:0xf
	v_mov_b32_dpp v120, v94 quad_perm:[1,0,3,2] row_mask:0xf bank_mask:0xf bound_ctrl:1
	v_cndmask_b32_e32 v120, v86, v120, vcc
	v_cvt_pk_bf16_f32 v96, v96, v120
	v_addc_co_u32_e64 v133, s[4:5], 0, v133, s[4:5]
	global_store_dword v[132:133], v96, off
	v_cndmask_b32_dpp v126, v82, v90, vcc quad_perm:[1,0,3,2] row_mask:0xf bank_mask:0xf
	v_mov_b32_dpp v109, v90 quad_perm:[1,0,3,2] row_mask:0xf bank_mask:0xf bound_ctrl:1
	v_cndmask_b32_e32 v109, v82, v109, vcc
	v_cvt_pk_bf16_f32 v126, v126, v109
	global_store_dword v[132:133], v126, off offset:256
	v_add_co_u32_e64 v132, s[4:5], s50, v132
	v_cndmask_b32_dpp v101, v87, v95, vcc quad_perm:[1,0,3,2] row_mask:0xf bank_mask:0xf
	v_mov_b32_dpp v118, v95 quad_perm:[1,0,3,2] row_mask:0xf bank_mask:0xf bound_ctrl:1
	v_cndmask_b32_e32 v118, v87, v118, vcc
	v_cvt_pk_bf16_f32 v101, v101, v118
	v_addc_co_u32_e64 v133, s[4:5], 0, v133, s[4:5]
	global_store_dword v[132:133], v101, off
	v_cndmask_b32_dpp v112, v83, v91, vcc quad_perm:[1,0,3,2] row_mask:0xf bank_mask:0xf
	v_mov_b32_dpp v105, v91 quad_perm:[1,0,3,2] row_mask:0xf bank_mask:0xf bound_ctrl:1
	v_cndmask_b32_e32 v105, v83, v105, vcc
	v_cvt_pk_bf16_f32 v112, v112, v105
	global_store_dword v[132:133], v112, off offset:256
	s_mov_b32 s50, 0x57c00
	v_add_co_u32_e64 v132, s[4:5], s50, v132
	v_cndmask_b32_dpp v97, v68, v76, vcc quad_perm:[1,0,3,2] row_mask:0xf bank_mask:0xf
	v_mov_b32_dpp v131, v76 quad_perm:[1,0,3,2] row_mask:0xf bank_mask:0xf bound_ctrl:1
	v_cndmask_b32_e32 v131, v68, v131, vcc
	v_cvt_pk_bf16_f32 v97, v97, v131
	v_addc_co_u32_e64 v133, s[4:5], 0, v133, s[4:5]
	global_store_dword v[132:133], v97, off
	v_cndmask_b32_dpp v122, v64, v72, vcc quad_perm:[1,0,3,2] row_mask:0xf bank_mask:0xf
	v_mov_b32_dpp v110, v72 quad_perm:[1,0,3,2] row_mask:0xf bank_mask:0xf bound_ctrl:1
	v_cndmask_b32_e32 v110, v64, v110, vcc
	v_cvt_pk_bf16_f32 v122, v122, v110
	global_store_dword v[132:133], v122, off offset:256
	s_mov_b32 s50, 0x6c00
	v_add_co_u32_e64 v132, s[4:5], s50, v132
	v_cndmask_b32_dpp v102, v69, v77, vcc quad_perm:[1,0,3,2] row_mask:0xf bank_mask:0xf
	v_mov_b32_dpp v114, v77 quad_perm:[1,0,3,2] row_mask:0xf bank_mask:0xf bound_ctrl:1
	v_cndmask_b32_e32 v114, v69, v114, vcc
	v_cvt_pk_bf16_f32 v102, v102, v114
	v_addc_co_u32_e64 v133, s[4:5], 0, v133, s[4:5]
	global_store_dword v[132:133], v102, off
	v_cndmask_b32_dpp v124, v65, v73, vcc quad_perm:[1,0,3,2] row_mask:0xf bank_mask:0xf
	v_mov_b32_dpp v106, v73 quad_perm:[1,0,3,2] row_mask:0xf bank_mask:0xf bound_ctrl:1
	v_cndmask_b32_e32 v106, v65, v106, vcc
	v_cvt_pk_bf16_f32 v124, v124, v106
	global_store_dword v[132:133], v124, off offset:256
	v_add_co_u32_e64 v132, s[4:5], s50, v132
	v_cndmask_b32_dpp v98, v70, v78, vcc quad_perm:[1,0,3,2] row_mask:0xf bank_mask:0xf
	v_mov_b32_dpp v125, v78 quad_perm:[1,0,3,2] row_mask:0xf bank_mask:0xf bound_ctrl:1
	v_cndmask_b32_e32 v125, v70, v125, vcc
	v_cvt_pk_bf16_f32 v98, v98, v125
	v_addc_co_u32_e64 v133, s[4:5], 0, v133, s[4:5]
	global_store_dword v[132:133], v98, off
	v_cndmask_b32_dpp v127, v66, v74, vcc quad_perm:[1,0,3,2] row_mask:0xf bank_mask:0xf
	v_mov_b32_dpp v111, v74 quad_perm:[1,0,3,2] row_mask:0xf bank_mask:0xf bound_ctrl:1
	v_cndmask_b32_e32 v111, v66, v111, vcc
	v_cvt_pk_bf16_f32 v127, v127, v111
	global_store_dword v[132:133], v127, off offset:256
	v_add_co_u32_e64 v132, s[4:5], s50, v132
	v_cndmask_b32_dpp v103, v71, v79, vcc quad_perm:[1,0,3,2] row_mask:0xf bank_mask:0xf
	v_mov_b32_dpp v119, v79 quad_perm:[1,0,3,2] row_mask:0xf bank_mask:0xf bound_ctrl:1
	v_cndmask_b32_e32 v119, v71, v119, vcc
	v_cvt_pk_bf16_f32 v103, v103, v119
	v_addc_co_u32_e64 v133, s[4:5], 0, v133, s[4:5]
; __device__ __forceinline__ float xor1f(float v) { return __int_as_float(__builtin_amdgcn_update_dpp(0, __float_as_int(v), 0xB1, 0xF, 0xF, true)); }
; template <int K, int EPI>
; __device__ __forceinline__ void gemm_tile(const u16* __restrict__ A, const u16* __restrict__ Bt, int brow, int bcol,
;                                           u16* Cb, int ldc, const float* R, float* Cf) {
;     ...
;   const int row0 = brow + wr * 64 + fq * 4, col0 = bcol + wc * 32 + fr;
;   if constexpr (EPI == 0) {
;     u16* cb = Cb + (size_t)row0 * ldc + col0;
; #pragma unroll
;     for (int ai = 0; ai < 2; ++ai)
; #pragma unroll
;       for (int m = 0; m < 4; ++m)
; #pragma unroll
;         for (int j = 0; j < 4; ++j) {
;           u16* cr = cb + (size_t)(ai * HALF + m * 16 + j) * ldc;
; #pragma unroll
;           for (int bj = 0; bj < 2; ++bj)
; #pragma unroll
;             for (int n = 0; n < 2; ++n) {
;               const float v = acc[ai][bj][m][n][j];
;               const float vn = xor1f(v);
;               if ((fr & 1) == 0) *(unsigned*)(cr + bj * HALF + n * 16) = cvtpk(v, vn);
;             }
;         }
	global_store_dword v[132:133], v103, off
	v_cndmask_b32_dpp v117, v67, v75, vcc quad_perm:[1,0,3,2] row_mask:0xf bank_mask:0xf
	v_mov_b32_dpp v107, v75 quad_perm:[1,0,3,2] row_mask:0xf bank_mask:0xf bound_ctrl:1
	v_cndmask_b32_e32 v107, v67, v107, vcc
	v_cvt_pk_bf16_f32 v117, v117, v107
	global_store_dword v[132:133], v117, off offset:256
	s_mov_b32 s50, 0x207c00
	v_add_co_u32_e64 v132, s[4:5], s50, v132
	v_cndmask_b32_dpp v99, v56, v60, vcc quad_perm:[1,0,3,2] row_mask:0xf bank_mask:0xf
	v_mov_b32_dpp v116, v60 quad_perm:[1,0,3,2] row_mask:0xf bank_mask:0xf bound_ctrl:1
	v_cndmask_b32_e32 v116, v56, v116, vcc
	v_cvt_pk_bf16_f32 v99, v99, v116
	v_addc_co_u32_e64 v133, s[4:5], 0, v133, s[4:5]
	global_store_dword v[132:133], v99, off
	v_cndmask_b32_dpp v123, v48, v52, vcc quad_perm:[1,0,3,2] row_mask:0xf bank_mask:0xf
	v_mov_b32_dpp v92, v52 quad_perm:[1,0,3,2] row_mask:0xf bank_mask:0xf bound_ctrl:1
	v_cndmask_b32_e32 v92, v48, v92, vcc
	v_cvt_pk_bf16_f32 v123, v123, v92
	global_store_dword v[132:133], v123, off offset:256
	s_mov_b32 s50, 0x6c00
	v_add_co_u32_e64 v132, s[4:5], s50, v132
	v_cndmask_b32_dpp v84, v57, v61, vcc quad_perm:[1,0,3,2] row_mask:0xf bank_mask:0xf
	v_mov_b32_dpp v115, v61 quad_perm:[1,0,3,2] row_mask:0xf bank_mask:0xf bound_ctrl:1
	v_cndmask_b32_e32 v115, v57, v115, vcc
	v_cvt_pk_bf16_f32 v84, v84, v115
	v_addc_co_u32_e64 v133, s[4:5], 0, v133, s[4:5]
	global_store_dword v[132:133], v84, off
	v_cndmask_b32_dpp v128, v49, v53, vcc quad_perm:[1,0,3,2] row_mask:0xf bank_mask:0xf
	v_mov_b32_dpp v88, v53 quad_perm:[1,0,3,2] row_mask:0xf bank_mask:0xf bound_ctrl:1
	v_cndmask_b32_e32 v88, v49, v88, vcc
	v_cvt_pk_bf16_f32 v128, v128, v88
	global_store_dword v[132:133], v128, off offset:256
	v_add_co_u32_e64 v132, s[4:5], s50, v132
	v_cndmask_b32_dpp v80, v58, v62, vcc quad_perm:[1,0,3,2] row_mask:0xf bank_mask:0xf
	v_mov_b32_dpp v121, v62 quad_perm:[1,0,3,2] row_mask:0xf bank_mask:0xf bound_ctrl:1
	v_cndmask_b32_e32 v121, v58, v121, vcc
	v_cvt_pk_bf16_f32 v80, v80, v121
	v_addc_co_u32_e64 v133, s[4:5], 0, v133, s[4:5]
	global_store_dword v[132:133], v80, off
	v_cndmask_b32_dpp v108, v50, v54, vcc quad_perm:[1,0,3,2] row_mask:0xf bank_mask:0xf
	v_mov_b32_dpp v93, v54 quad_perm:[1,0,3,2] row_mask:0xf bank_mask:0xf bound_ctrl:1
	v_cndmask_b32_e32 v93, v50, v93, vcc
	v_cvt_pk_bf16_f32 v108, v108, v93
	global_store_dword v[132:133], v108, off offset:256
	v_add_co_u32_e64 v132, s[4:5], s50, v132
	v_cndmask_b32_dpp v85, v59, v63, vcc quad_perm:[1,0,3,2] row_mask:0xf bank_mask:0xf
	v_mov_b32_dpp v100, v63 quad_perm:[1,0,3,2] row_mask:0xf bank_mask:0xf bound_ctrl:1
	v_cndmask_b32_e32 v100, v59, v100, vcc
	v_cvt_pk_bf16_f32 v85, v85, v100
	v_addc_co_u32_e64 v133, s[4:5], 0, v133, s[4:5]
	global_store_dword v[132:133], v85, off
	v_cndmask_b32_dpp v113, v51, v55, vcc quad_perm:[1,0,3,2] row_mask:0xf bank_mask:0xf
	v_mov_b32_dpp v89, v55 quad_perm:[1,0,3,2] row_mask:0xf bank_mask:0xf bound_ctrl:1
	v_cndmask_b32_e32 v89, v51, v89, vcc
	v_cvt_pk_bf16_f32 v113, v113, v89
	global_store_dword v[132:133], v113, off offset:256
	s_mov_b32 s50, 0x57c00
	v_add_co_u32_e64 v132, s[4:5], s50, v132
	v_cndmask_b32_dpp v81, v40, v44, vcc quad_perm:[1,0,3,2] row_mask:0xf bank_mask:0xf
	v_mov_b32_dpp v130, v44 quad_perm:[1,0,3,2] row_mask:0xf bank_mask:0xf bound_ctrl:1
	v_cndmask_b32_e32 v130, v40, v130, vcc
	v_cvt_pk_bf16_f32 v81, v81, v130
	v_addc_co_u32_e64 v133, s[4:5], 0, v133, s[4:5]
	global_store_dword v[132:133], v81, off
	v_cndmask_b32_dpp v104, v32, v36, vcc quad_perm:[1,0,3,2] row_mask:0xf bank_mask:0xf
	v_mov_b32_dpp v94, v36 quad_perm:[1,0,3,2] row_mask:0xf bank_mask:0xf bound_ctrl:1
	v_cndmask_b32_e32 v94, v32, v94, vcc
	v_cvt_pk_bf16_f32 v104, v104, v94
	global_store_dword v[132:133], v104, off offset:256
	s_mov_b32 s50, 0x6c00
	v_add_co_u32_e64 v132, s[4:5], s50, v132
	v_cndmask_b32_dpp v86, v41, v45, vcc quad_perm:[1,0,3,2] row_mask:0xf bank_mask:0xf
	v_mov_b32_dpp v96, v45 quad_perm:[1,0,3,2] row_mask:0xf bank_mask:0xf bound_ctrl:1
	v_cndmask_b32_e32 v96, v41, v96, vcc
	v_cvt_pk_bf16_f32 v86, v86, v96
	v_addc_co_u32_e64 v133, s[4:5], 0, v133, s[4:5]
	global_store_dword v[132:133], v86, off
	v_cndmask_b32_dpp v120, v33, v37, vcc quad_perm:[1,0,3,2] row_mask:0xf bank_mask:0xf
	v_mov_b32_dpp v90, v37 quad_perm:[1,0,3,2] row_mask:0xf bank_mask:0xf bound_ctrl:1
	v_cndmask_b32_e32 v90, v33, v90, vcc
	v_cvt_pk_bf16_f32 v120, v120, v90
	global_store_dword v[132:133], v120, off offset:256
	v_add_co_u32_e64 v132, s[4:5], s50, v132
	v_cndmask_b32_dpp v82, v42, v46, vcc quad_perm:[1,0,3,2] row_mask:0xf bank_mask:0xf
	v_mov_b32_dpp v126, v46 quad_perm:[1,0,3,2] row_mask:0xf bank_mask:0xf bound_ctrl:1
	v_cndmask_b32_e32 v126, v42, v126, vcc
	v_cvt_pk_bf16_f32 v82, v82, v126
	v_addc_co_u32_e64 v133, s[4:5], 0, v133, s[4:5]
	global_store_dword v[132:133], v82, off
	v_cndmask_b32_dpp v109, v34, v38, vcc quad_perm:[1,0,3,2] row_mask:0xf bank_mask:0xf
	v_mov_b32_dpp v95, v38 quad_perm:[1,0,3,2] row_mask:0xf bank_mask:0xf bound_ctrl:1
	v_cndmask_b32_e32 v95, v34, v95, vcc
	v_cvt_pk_bf16_f32 v109, v109, v95
	global_store_dword v[132:133], v109, off offset:256
	v_add_co_u32_e64 v132, s[4:5], s50, v132
	v_cndmask_b32_dpp v87, v43, v47, vcc quad_perm:[1,0,3,2] row_mask:0xf bank_mask:0xf
	v_mov_b32_dpp v101, v47 quad_perm:[1,0,3,2] row_mask:0xf bank_mask:0xf bound_ctrl:1
	v_cndmask_b32_e32 v101, v43, v101, vcc
	v_cvt_pk_bf16_f32 v87, v87, v101
	v_addc_co_u32_e64 v133, s[4:5], 0, v133, s[4:5]
	global_store_dword v[132:133], v87, off
	v_cndmask_b32_dpp v118, v35, v39, vcc quad_perm:[1,0,3,2] row_mask:0xf bank_mask:0xf
; __device__ __forceinline__ float xor1f(float v) { return __int_as_float(__builtin_amdgcn_update_dpp(0, __float_as_int(v), 0xB1, 0xF, 0xF, true)); }
; template <int K, int EPI>
; __device__ __forceinline__ void gemm_tile(const u16* __restrict__ A, const u16* __restrict__ Bt, int brow, int bcol,
;                                           u16* Cb, int ldc, const float* R, float* Cf) {
;     ...
;   const int row0 = brow + wr * 64 + fq * 4, col0 = bcol + wc * 32 + fr;
;   if constexpr (EPI == 0) {
;     u16* cb = Cb + (size_t)row0 * ldc + col0;
; #pragma unroll
;     for (int ai = 0; ai < 2; ++ai)
; #pragma unroll
;       for (int m = 0; m < 4; ++m)
; #pragma unroll
;         for (int j = 0; j < 4; ++j) {
;           u16* cr = cb + (size_t)(ai * HALF + m * 16 + j) * ldc;
; #pragma unroll
;           for (int bj = 0; bj < 2; ++bj)
; #pragma unroll
;             for (int n = 0; n < 2; ++n) {
;               const float v = acc[ai][bj][m][n][j];
;               const float vn = xor1f(v);
;               if ((fr & 1) == 0) *(unsigned*)(cr + bj * HALF + n * 16) = cvtpk(v, vn);
;             }
;         }
	v_mov_b32_dpp v91, v39 quad_perm:[1,0,3,2] row_mask:0xf bank_mask:0xf bound_ctrl:1
	v_cndmask_b32_e32 v91, v35, v91, vcc
	v_cvt_pk_bf16_f32 v118, v118, v91
	global_store_dword v[132:133], v118, off offset:256
	s_mov_b32 s50, 0x57c00
	v_add_co_u32_e64 v132, s[4:5], s50, v132
	v_cndmask_b32_dpp v83, v24, v28, vcc quad_perm:[1,0,3,2] row_mask:0xf bank_mask:0xf
	v_mov_b32_dpp v112, v28 quad_perm:[1,0,3,2] row_mask:0xf bank_mask:0xf bound_ctrl:1
	v_cndmask_b32_e32 v112, v24, v112, vcc
	v_cvt_pk_bf16_f32 v83, v83, v112
	v_addc_co_u32_e64 v133, s[4:5], 0, v133, s[4:5]
	global_store_dword v[132:133], v83, off
	v_cndmask_b32_dpp v105, v16, v20, vcc quad_perm:[1,0,3,2] row_mask:0xf bank_mask:0xf
	v_mov_b32_dpp v76, v20 quad_perm:[1,0,3,2] row_mask:0xf bank_mask:0xf bound_ctrl:1
	v_cndmask_b32_e32 v76, v16, v76, vcc
	v_cvt_pk_bf16_f32 v105, v105, v76
	global_store_dword v[132:133], v105, off offset:256
	s_mov_b32 s50, 0x6c00
	v_add_co_u32_e64 v132, s[4:5], s50, v132
	v_cndmask_b32_dpp v68, v25, v29, vcc quad_perm:[1,0,3,2] row_mask:0xf bank_mask:0xf
	v_mov_b32_dpp v97, v29 quad_perm:[1,0,3,2] row_mask:0xf bank_mask:0xf bound_ctrl:1
	v_cndmask_b32_e32 v97, v25, v97, vcc
	v_cvt_pk_bf16_f32 v68, v68, v97
	v_addc_co_u32_e64 v133, s[4:5], 0, v133, s[4:5]
	global_store_dword v[132:133], v68, off
	v_cndmask_b32_dpp v131, v17, v21, vcc quad_perm:[1,0,3,2] row_mask:0xf bank_mask:0xf
	v_mov_b32_dpp v72, v21 quad_perm:[1,0,3,2] row_mask:0xf bank_mask:0xf bound_ctrl:1
	v_cndmask_b32_e32 v72, v17, v72, vcc
	v_cvt_pk_bf16_f32 v131, v131, v72
	global_store_dword v[132:133], v131, off offset:256
	v_add_co_u32_e64 v132, s[4:5], s50, v132
	v_cndmask_b32_dpp v64, v26, v30, vcc quad_perm:[1,0,3,2] row_mask:0xf bank_mask:0xf
	v_mov_b32_dpp v122, v30 quad_perm:[1,0,3,2] row_mask:0xf bank_mask:0xf bound_ctrl:1
	v_cndmask_b32_e32 v122, v26, v122, vcc
	v_cvt_pk_bf16_f32 v64, v64, v122
	v_addc_co_u32_e64 v133, s[4:5], 0, v133, s[4:5]
	global_store_dword v[132:133], v64, off
	v_cndmask_b32_dpp v110, v18, v22, vcc quad_perm:[1,0,3,2] row_mask:0xf bank_mask:0xf
	v_mov_b32_dpp v77, v22 quad_perm:[1,0,3,2] row_mask:0xf bank_mask:0xf bound_ctrl:1
	v_cndmask_b32_e32 v77, v18, v77, vcc
	v_cvt_pk_bf16_f32 v110, v110, v77
	global_store_dword v[132:133], v110, off offset:256
	v_add_co_u32_e64 v132, s[4:5], s50, v132
	v_cndmask_b32_dpp v69, v27, v31, vcc quad_perm:[1,0,3,2] row_mask:0xf bank_mask:0xf
	v_mov_b32_dpp v102, v31 quad_perm:[1,0,3,2] row_mask:0xf bank_mask:0xf bound_ctrl:1
	v_cndmask_b32_e32 v102, v27, v102, vcc
	v_cvt_pk_bf16_f32 v69, v69, v102
	v_addc_co_u32_e64 v133, s[4:5], 0, v133, s[4:5]
	global_store_dword v[132:133], v69, off
	v_cndmask_b32_dpp v114, v19, v23, vcc quad_perm:[1,0,3,2] row_mask:0xf bank_mask:0xf
	v_mov_b32_dpp v73, v23 quad_perm:[1,0,3,2] row_mask:0xf bank_mask:0xf bound_ctrl:1
	v_cndmask_b32_e32 v73, v19, v73, vcc
	v_cvt_pk_bf16_f32 v114, v114, v73
	global_store_dword v[132:133], v114, off offset:256
	s_mov_b32 s50, 0x57c00
	v_add_co_u32_e64 v132, s[4:5], s50, v132
	v_cndmask_b32_dpp v65, v8, v12, vcc quad_perm:[1,0,3,2] row_mask:0xf bank_mask:0xf
	v_mov_b32_dpp v124, v12 quad_perm:[1,0,3,2] row_mask:0xf bank_mask:0xf bound_ctrl:1
	v_cndmask_b32_e32 v124, v8, v124, vcc
	v_cvt_pk_bf16_f32 v65, v65, v124
	v_addc_co_u32_e64 v133, s[4:5], 0, v133, s[4:5]
	global_store_dword v[132:133], v65, off
	v_cndmask_b32_dpp v106, v0, v4, vcc quad_perm:[1,0,3,2] row_mask:0xf bank_mask:0xf
	v_mov_b32_dpp v78, v4 quad_perm:[1,0,3,2] row_mask:0xf bank_mask:0xf bound_ctrl:1
	v_cndmask_b32_e32 v78, v0, v78, vcc
	v_cvt_pk_bf16_f32 v106, v106, v78
	global_store_dword v[132:133], v106, off offset:256
	s_mov_b32 s50, 0x6c00
	v_add_co_u32_e64 v132, s[4:5], s50, v132
	v_cndmask_b32_dpp v70, v9, v13, vcc quad_perm:[1,0,3,2] row_mask:0xf bank_mask:0xf
	v_mov_b32_dpp v98, v13 quad_perm:[1,0,3,2] row_mask:0xf bank_mask:0xf bound_ctrl:1
	v_cndmask_b32_e32 v98, v9, v98, vcc
	v_cvt_pk_bf16_f32 v70, v70, v98
	v_addc_co_u32_e64 v133, s[4:5], 0, v133, s[4:5]
	global_store_dword v[132:133], v70, off
	v_cndmask_b32_dpp v125, v1, v5, vcc quad_perm:[1,0,3,2] row_mask:0xf bank_mask:0xf
	v_mov_b32_dpp v74, v5 quad_perm:[1,0,3,2] row_mask:0xf bank_mask:0xf bound_ctrl:1
	v_cndmask_b32_e32 v74, v1, v74, vcc
	v_cvt_pk_bf16_f32 v125, v125, v74
	global_store_dword v[132:133], v125, off offset:256
	v_add_co_u32_e64 v132, s[4:5], s50, v132
	v_cndmask_b32_dpp v66, v10, v14, vcc quad_perm:[1,0,3,2] row_mask:0xf bank_mask:0xf
	v_mov_b32_dpp v127, v14 quad_perm:[1,0,3,2] row_mask:0xf bank_mask:0xf bound_ctrl:1
	v_cndmask_b32_e32 v127, v10, v127, vcc
	v_cvt_pk_bf16_f32 v66, v66, v127
	v_addc_co_u32_e64 v133, s[4:5], 0, v133, s[4:5]
	global_store_dword v[132:133], v66, off
	v_cndmask_b32_dpp v111, v2, v6, vcc quad_perm:[1,0,3,2] row_mask:0xf bank_mask:0xf
	v_mov_b32_dpp v79, v6 quad_perm:[1,0,3,2] row_mask:0xf bank_mask:0xf bound_ctrl:1
	v_cndmask_b32_e32 v79, v2, v79, vcc
	v_cvt_pk_bf16_f32 v111, v111, v79
	global_store_dword v[132:133], v111, off offset:256
	v_add_co_u32_e64 v132, s[4:5], s50, v132
	v_cndmask_b32_dpp v71, v11, v15, vcc quad_perm:[1,0,3,2] row_mask:0xf bank_mask:0xf
	v_mov_b32_dpp v103, v15 quad_perm:[1,0,3,2] row_mask:0xf bank_mask:0xf bound_ctrl:1
	v_cndmask_b32_e32 v103, v11, v103, vcc
	v_cvt_pk_bf16_f32 v71, v71, v103
	v_addc_co_u32_e64 v133, s[4:5], 0, v133, s[4:5]
	global_store_dword v[132:133], v71, off
	v_cndmask_b32_dpp v119, v3, v7, vcc quad_perm:[1,0,3,2] row_mask:0xf bank_mask:0xf
	v_mov_b32_dpp v75, v7 quad_perm:[1,0,3,2] row_mask:0xf bank_mask:0xf bound_ctrl:1
	v_cndmask_b32_e32 v75, v3, v75, vcc
	v_cvt_pk_bf16_f32 v119, v119, v75
	global_store_dword v[132:133], v119, off offset:256
	s_branch .LBB0_1608
